# P1b fp6 operands repacked: 96 useful bytes per row and K-tile in 3/4 of the 128-byte lines (second parts of rows r and r+64 share a line half, first parts of rows 64..127 two per line); the i=1 LDS-DM
# speedup vs baseline: 1.0126x; 1.0086x over previous
; #define LAS __attribute__((address_space(3)))
; #define LDS_WAIT() asm volatile("s_waitcnt lgkmcnt(0)" ::: "memory")
; __device__ __forceinline__ int lane_id() { int l; asm volatile("v_mbcnt_lo_u32_b32 %0, -1, 0\n\tv_mbcnt_hi_u32_b32 %0, -1, %0" : "=v"(l)); return l; }
; __device__ __forceinline__ void p0_transpose_pair_fp6(const float* W, int K, int N, int ncol0, unsigned char* WT6, int row0, LAS float* scr, int kb, int lane) {
;     LAS unsigned* stg = (LAS unsigned*)(scr + 64 * 33);
;     const int n = lane & 31, grp = lane >> 5;
; #pragma unroll
;     for (int h = 0; h < 2; ++h) {
;         const int k0 = 64 * (kb + h);
; #pragma unroll 8
;         for (int i = 0; i < 8; ++i) { const int kk = 8 * i + (lane >> 3), n4 = (lane & 7) * 4;
;         const f32x4 v4 = *(const f32x4*)(W + (size_t)(k0 + kk) * N + ncol0 + n4); LAS float* d4 = scr + kk * 33 + n4; d4[0] = v4[0]; d4[1] = v4[1]; d4[2] = v4[2]; d4[3] = v4[3]; }
;         LDS_WAIT(); asm volatile("" ::: "memory");
;         f32x16v a, b;
; #pragma unroll
;         for (int i = 0; i < 16; ++i) { a[i] = __builtin_amdgcn_fmed3f(scr[(grp * 32 + i) * 33 + n] * W6_SCALE, -7.5f, 7.5f); b[i] = __builtin_amdgcn_fmed3f(scr[(grp * 32 + 16 + i) * 33 + n] * W6_SCALE, -7.5f, 7.5f); }
;         const u32x6v p = __builtin_amdgcn_cvt_scalef32_2xpk16_fp6_f32(a, b, 1.0f);
;         const int fq = h * 2 + grp;
;         *(LAS u32x4*)(stg + n * 36 + fq * 4) = (u32x4){p[0], p[1], p[2], p[3]};
;         *(LAS u32x4*)(stg + n * 36 + 16 + fq * 4) = (u32x4){p[4], p[5], 0u, 0u};
; __device__ __forceinline__ void p0_prologue(const Frame& F) {
;     int ptid = F.wave * 64 + lane_id(); asm volatile("" : "+v"(ptid));
;     const int plane = ptid & 63;
;     LAS float* scr = (LAS float*)(F.lds + F.wave * 16384);
;     const int gw = F.bx * NWAVES + F.wave, NGW = F.G * NWAVES;
;     constexpr int NB6 = 576, NBO = 512, I_6 = (DM / 128) * NB6, I_IN = (DM / 64) * NBO, I_A = (EA / 64) * (DM / 32), I_B = I_A, I_O = (DM / 64) * (DM / 32);
;     constexpr int NITEMS = I_6 + I_IN + I_A + I_B + I_O;
;     for (int it = gw; it < NITEMS; it += NGW) {
;         int r = it;
;         if (r < I_6) { const int kt = r / NB6, nb = r % NB6;
;             if (nb < 384) p0_transpose_pair_fp6(F.w_in, DM, NIN, 6144 + 32 * nb, F.WinT8, 32 * nb, scr, 2 * kt, plane);
.LBB0_11:
	s_add_u32 s64, s40, 0x6000000
	s_addc_u32 s65, s41, 0
	s_add_u32 s60, s40, 0x9000000
	s_addc_u32 s61, s41, 0
	s_add_u32 s52, s40, 0x7d000000
	s_addc_u32 s53, s41, 0
	s_add_u32 s56, s40, 0x80000000
	s_addc_u32 s57, s41, 0
	s_add_u32 s48, s40, 0x2000000
	s_addc_u32 s49, s41, 0
	s_add_u32 s44, s40, 0x3000000
	s_addc_u32 s45, s41, 0
	s_add_u32 s28, s40, 0x4000000
	s_addc_u32 s29, s41, 0
	s_cmp_lt_i32 s42, 1
	s_cselect_b64 s[0:1], -1, 0
	s_cmp_gt_i32 s43, 0
	s_cselect_b64 s[4:5], -1, 0
	s_and_b64 s[46:47], s[0:1], s[4:5]
	s_andn2_b64 vcc, exec, s[46:47]
	s_cbranch_vccnz .LBB0_60
	s_lshl_b32 s0, s97, 14
	v_mbcnt_lo_u32_b32 v0, -1, 0
	v_mbcnt_hi_u32_b32 v0, -1, v0
	s_add_i32 s3, s0, 0
	v_add_u32_e32 v66, s74, v0
	s_lshl_b32 s0, s2, 3
	s_add_i32 s50, s97, s0
	v_and_b32_e32 v35, 63, v66
	s_lshl_b32 s54, s34, 3
	s_mov_b32 s1, 0
	s_cmp_gt_i32 s50, 0x107ff
	v_lshlrev_b32_e32 v68, 3, v35
	s_cbranch_scc1 .LBB0_49
	v_lshrrev_b32_e32 v64, 3, v35
	v_and_b32_e32 v36, 56, v68
	v_mul_u32_u24_e32 v1, 0x84, v36
	v_lshlrev_b32_e32 v2, 2, v64
	v_lshlrev_b32_e32 v0, 2, v35
	v_add3_u32 v74, s3, v1, v2
	v_and_b32_e32 v1, 31, v66
	v_and_b32_e32 v3, 32, v66
	v_and_b32_e32 v34, 28, v0
	v_mul_u32_u24_e32 v6, 0x90, v1
	v_mul_u32_u24_e32 v3, 0x84, v3
	v_lshlrev_b32_e32 v1, 2, v1
	v_mov_b32_e32 v33, 0
	v_lshlrev_b32_e32 v0, 2, v34
	v_add3_u32 v75, s3, v3, v1
	v_and_b32_e32 v1, 16, v2
	v_add_u32_e32 v4, s3, v0
	v_mul_u32_u24_e32 v5, 0x84, v64
	v_mov_b32_e32 v37, v33
	v_add3_u32 v76, s3, v6, v1
	v_bfe_u32 v120, v66, 3, 2
	v_sub_u32_e32 v120, 0, v120
	v_and_b32_e32 v120, 3, v120
	v_lshrrev_b32_e32 v121, 4, v1
	v_xor_b32_e32 v120, v121, v120
	v_lshlrev_b32_e32 v120, 4, v120
	v_sub_u32_e32 v122, v76, v1
	v_xor_b32_e32 v121, 32, v120
	v_add_u32_e32 v120, v122, v120
	v_add_u32_e32 v121, v122, v121
	v_subrev_u32_e32 v121, 32, v121
	v_lshrrev_b32_e32 v123, 1, v1
	v_add_u32_e32 v123, v122, v123
	v_bfe_u32 v126, v66, 4, 1
	v_lshlrev_b32_e32 v126, 4, v126
	v_add_u32_e32 v122, v123, v126
	v_sub_u32_e32 v123, v123, v126
	v_add_u32_e32 v123, 16, v123
	v_lshlrev_b32_e32 v1, 4, v35
	v_readlane_b32 s4, v255, 0
	v_and_b32_e32 v32, 0x70, v1
	v_mov_b32_e32 v1, v33
	v_readlane_b32 s5, v255, 1
	v_readlane_b32 s6, v255, 2
	v_readlane_b32 s7, v255, 3
	v_readlane_b32 s8, v255, 4
	v_readlane_b32 s9, v255, 5
	v_readlane_b32 s10, v255, 6
	v_readlane_b32 s11, v255, 7
	v_lshlrev_b32_e32 v2, 1, v36
	v_mov_b32_e32 v3, v33
	v_lshl_add_u64 v[44:45], s[44:45], 0, v[36:37]
	v_add_u32_e32 v37, v4, v5
	v_or_b32_e32 v65, 8, v64
	v_or_b32_e32 v67, 16, v64
	v_or_b32_e32 v69, 24, v64
	v_or_b32_e32 v70, 32, v64
	v_or_b32_e32 v71, 40, v64
	v_or_b32_e32 v72, 48, v64
	v_or_b32_e32 v73, 56, v64
	v_add_u32_e32 v77, s3, v32
	v_mul_u32_u24_e32 v78, 0x90, v64
	v_lshl_add_u64 v[38:39], s[8:9], 0, v[0:1]
	v_lshl_add_u64 v[40:41], s[28:29], 0, v[2:3]
	v_lshl_add_u64 v[42:43], s[6:7], 0, v[0:1]
	v_lshl_add_u64 v[46:47], s[4:5], 0, v[0:1]
	v_lshl_add_u64 v[48:49], s[48:49], 0, v[2:3]
	v_lshl_add_u64 v[50:51], s[16:17], 0, v[0:1]
	v_lshl_add_u64 v[52:53], s[64:65], 0, v[2:3]
	v_lshl_add_u64 v[54:55], s[60:61], 0, v[32:33]
	s_lshl_b32 s10, s50, 5
	s_lshl_b32 s11, s54, 5
	s_lshl_b32 s33, s50, 6
	s_lshl_b32 s35, s54, 6
	v_add_u32_e32 v79, 0x420, v37
	v_add_u32_e32 v80, 0x428, v37
	v_add_u32_e32 v81, 0x840, v37
	v_add_u32_e32 v82, 0x848, v37
	v_add_u32_e32 v83, 0xc60, v37
	v_add_u32_e32 v84, 0xc68, v37
	v_add_u32_e32 v85, 0x1080, v37
	v_add_u32_e32 v86, 0x1088, v37
	s_mov_b32 s51, 0x8800
	s_mov_b64 s[4:5], 0x12000
	s_mov_b32 s55, 0xc0c00000
	s_mov_b64 s[6:7], 0xc000
	s_mov_b32 s68, 0x22000
	s_mov_b32 s69, 0xc0f00000
	s_mov_b64 s[8:9], 0x6000
	v_add_u32_e32 v87, 0x14a0, v37
	v_add_u32_e32 v88, 0x14a8, v37
	v_add_u32_e32 v89, 0x18c0, v37
	v_add_u32_e32 v90, 0x18c8, v37
	v_add_u32_e32 v91, 0x1ce0, v37
	v_add_u32_e32 v92, 0x1ce8, v37
	v_mov_b32_e32 v93, 0x40c00000
	s_mov_b32 s70, s50
	v_mov_b32_e32 v94, 0x40f00000
	s_branch .LBB0_15

; #define LAS __attribute__((address_space(3)))
; #define LDS_WAIT() asm volatile("s_waitcnt lgkmcnt(0)" ::: "memory")
;     __device__ __forceinline__ unsigned a(const pg8::Unit& u) const { return (unsigned)u.pm * (256u * K * 2u); }
;     __device__ __forceinline__ unsigned a(const pg8::Unit& u) const { return (unsigned)u.pm * (256u * K * 2u); }
;     __device__ __forceinline__ unsigned a(const pg8::Unit& u) const { return (unsigned)u.pm * (256u * K * 2u); }
;     __device__ __forceinline__ unsigned a(const pg8::Unit& u) const { return (unsigned)u.pm * (256u * K * 2u); }
;     __device__ __forceinline__ unsigned a(const pg8::Unit& u) const { return (unsigned)u.pm * (256u * K * 2u); }
; __device__ __forceinline__ void p0_transpose_pair_fp6(const float* W, int K, int N, int ncol0, unsigned char* WT6, int row0, LAS float* scr, int kb, int lane) {
;     LAS unsigned* stg = (LAS unsigned*)(scr + 64 * 33);
;     const int n = lane & 31, grp = lane >> 5;
; #pragma unroll
;     for (int h = 0; h < 2; ++h) {
;         const int k0 = 64 * (kb + h);
; #pragma unroll 8
;         for (int i = 0; i < 8; ++i) { const int kk = 8 * i + (lane >> 3), n4 = (lane & 7) * 4;
;         const f32x4 v4 = *(const f32x4*)(W + (size_t)(k0 + kk) * N + ncol0 + n4); LAS float* d4 = scr + kk * 33 + n4; d4[0] = v4[0]; d4[1] = v4[1]; d4[2] = v4[2]; d4[3] = v4[3]; }
;         LDS_WAIT(); asm volatile("" ::: "memory");
;         f32x16v a, b;
; #pragma unroll
;         for (int i = 0; i < 16; ++i) { a[i] = __builtin_amdgcn_fmed3f(scr[(grp * 32 + i) * 33 + n] * W6_SCALE, -7.5f, 7.5f); b[i] = __builtin_amdgcn_fmed3f(scr[(grp * 32 + 16 + i) * 33 + n] * W6_SCALE, -7.5f, 7.5f); }
; __device__ __forceinline__ void p0_prologue(const Frame& F) {
;     ...
;         if (r < I_6) { const int kt = r / NB6, nb = r % NB6;
;             if (nb < 384) p0_transpose_pair_fp6(F.w_in, DM, NIN, 6144 + 32 * nb, F.WinT8, 32 * nb, scr, 2 * kt, plane);
;             else          p0_transpose_pair_fp6(F.w_in, DM, NIN, 24576 + 32 * (nb - 384), F.WinT8, 12288 + 32 * (nb - 384), scr, 2 * kt, plane);
.LBB0_44:
	s_andn2_b64 vcc, exec, s[58:59]
	s_cbranch_vccnz .LBB0_14
	s_mul_hi_i32 s0, s70, 0x38e38e39
	s_lshr_b32 s58, s0, 31
	s_ashr_i32 s0, s0, 7
	s_add_i32 s0, s0, s58
	s_mul_i32 s58, s0, 0xfffffdc0
	s_add_i32 s59, s70, s58
	s_mul_i32 s58, s0, 0xffffb800
	s_add_i32 s62, s10, s58
	s_lshl_b32 s58, s0, 7
	v_or_b32_e32 v0, s58, v64
	v_mad_i64_i32 v[60:61], s[66:67], v0, s68, 0
	v_or_b32_e32 v0, s58, v65
	v_mad_i64_i32 v[58:59], s[66:67], v0, s68, 0
	s_cmpk_gt_i32 s59, 0x17f
	s_mov_b64 s[66:67], -1
	v_or_b32_e32 v104, s58, v67
	v_or_b32_e32 v103, s58, v69
	v_or_b32_e32 v102, s58, v70
	v_or_b32_e32 v101, s58, v71
	v_or_b32_e32 v100, s58, v72
	v_or_b32_e32 v99, s58, v73
	v_lshlrev_b32_e32 v32, 2, v34
	v_add_u32_e32 v98, 0x800, v75
	v_add_u32_e32 v97, 0x400, v75
	v_add_u32_e32 v96, 0xc00, v75
	v_add_u32_e32 v95, v77, v78
	v_lshrrev_b32_e32 v124, 1, v66
	v_and_b32_e32 v124, v124, v66
	v_bfe_u32 v124, v124, 1, 1
	v_lshlrev_b32_e32 v125, 5, v124
	v_sub_u32_e32 v124, v95, v125
	v_add_u32_e32 v56, s62, v64
	s_cbranch_scc0 .LBB0_47
	s_mov_b32 s63, s1
	s_lshl_b64 s[66:67], s[62:63], 2
	s_add_u32 s66, s16, s66
	s_addc_u32 s67, s17, s67
	v_lshl_add_u64 v[0:1], s[66:67], 0, v[32:33]
	v_lshl_add_u64 v[62:63], v[0:1], 0, s[6:7]
	v_lshl_add_u64 v[0:1], v[62:63], 0, v[60:61]
	v_lshl_add_u64 v[4:5], v[62:63], 0, v[58:59]
	v_mad_i64_i32 v[8:9], s[66:67], v104, s68, v[62:63]
	v_mad_i64_i32 v[12:13], s[66:67], v103, s68, v[62:63]
	v_mad_i64_i32 v[16:17], s[66:67], v102, s68, v[62:63]
	v_mad_i64_i32 v[20:21], s[66:67], v101, s68, v[62:63]
	global_load_dwordx4 v[0:3], v[0:1], off
	s_nop 0
	global_load_dwordx4 v[4:7], v[4:5], off
	s_nop 0
	global_load_dwordx4 v[8:11], v[8:9], off
	s_nop 0
	global_load_dwordx4 v[12:15], v[12:13], off
	s_nop 0
	global_load_dwordx4 v[16:19], v[16:17], off
	s_nop 0
	global_load_dwordx4 v[20:23], v[20:21], off
	v_mad_i64_i32 v[24:25], s[66:67], v100, s68, v[62:63]
	global_load_dwordx4 v[24:27], v[24:25], off
	v_mad_i64_i32 v[28:29], s[66:67], v99, s68, v[62:63]
	global_load_dwordx4 v[28:31], v[28:29], off
	s_or_b32 s0, s58, 64
	s_ashr_i32 s59, s58, 31
	v_mov_b32_e32 v57, v33
	s_waitcnt vmcnt(7)
	ds_write2_b32 v37, v0, v1 offset1:1
	ds_write2_b32 v37, v2, v3 offset0:2 offset1:3
	s_waitcnt vmcnt(6)
	ds_write2_b32 v79, v4, v5 offset1:1
	ds_write2_b32 v80, v6, v7 offset1:1
	s_waitcnt vmcnt(5)
	ds_write2_b32 v81, v8, v9 offset1:1
	ds_write2_b32 v82, v10, v11 offset1:1
	s_waitcnt vmcnt(4)
	ds_write2_b32 v83, v12, v13 offset1:1
	ds_write2_b32 v84, v14, v15 offset1:1
	s_waitcnt vmcnt(3)
	ds_write2_b32 v85, v16, v17 offset1:1
	ds_write2_b32 v86, v18, v19 offset1:1
	s_waitcnt vmcnt(2)
	ds_write2_b32 v87, v20, v21 offset1:1
	ds_write2_b32 v88, v22, v23 offset1:1
	s_waitcnt vmcnt(1)
	ds_write2_b32 v89, v24, v25 offset1:1
	ds_write2_b32 v90, v26, v27 offset1:1
	s_waitcnt vmcnt(0)
	ds_write2_b32 v91, v28, v29 offset1:1
	ds_write2_b32 v92, v30, v31 offset1:1
	s_waitcnt lgkmcnt(0)
	ds_read2_b32 v[0:1], v75 offset1:33
	ds_read2_b32 v[2:3], v98 offset0:16 offset1:49
	ds_read2_b32 v[4:5], v75 offset0:66 offset1:99
	ds_read2_b32 v[6:7], v98 offset0:82 offset1:115
	ds_read2_b32 v[8:9], v75 offset0:132 offset1:165
	ds_read2_b32 v[10:11], v98 offset0:148 offset1:181
	ds_read2_b32 v[12:13], v75 offset0:198 offset1:231
	ds_read2_b32 v[14:15], v98 offset0:214 offset1:247
	ds_read2_b32 v[16:17], v97 offset0:8 offset1:41
	ds_read2_b32 v[18:19], v96 offset0:24 offset1:57
	ds_read2_b32 v[26:27], v97 offset0:74 offset1:107
	ds_read2_b32 v[28:29], v96 offset0:90 offset1:123
	s_waitcnt lgkmcnt(4)
	v_mul_f32_e32 v14, 0x43000000, v14
	v_mul_f32_e32 v15, 0x43000000, v15
	v_med3_f32 v22, v14, s69, v94
	v_med3_f32 v23, v15, s69, v94
	ds_read2_b32 v[14:15], v96 offset0:156 offset1:189
	v_mul_f32_e32 v2, 0x43000000, v2
	v_mul_f32_e32 v3, 0x43000000, v3
	v_mul_f32_e32 v4, 0x43000000, v4
	v_mul_f32_e32 v6, 0x43000000, v6
	v_mul_f32_e32 v5, 0x43000000, v5
	v_mul_f32_e32 v7, 0x43000000, v7
	v_mul_f32_e32 v8, 0x43000000, v8
	v_mul_f32_e32 v9, 0x43000000, v9
	v_mul_f32_e32 v12, 0x43000000, v12
	v_mul_f32_e32 v13, 0x43000000, v13
	s_waitcnt lgkmcnt(4)
	v_mul_f32_e32 v24, 0x43000000, v16
	s_waitcnt lgkmcnt(3)
	v_mul_f32_e32 v25, 0x43000000, v18
	v_mul_f32_e32 v30, 0x43000000, v17
	v_mul_f32_e32 v31, 0x43000000, v19
	ds_read2_b32 v[106:107], v96 offset0:222 offset1:255
	v_med3_f32 v16, v2, s69, v94
	v_med3_f32 v17, v3, s69, v94
	v_med3_f32 v2, v4, s69, v94
	v_med3_f32 v18, v6, s69, v94
	v_med3_f32 v3, v5, s69, v94
	v_med3_f32 v19, v7, s69, v94
	v_med3_f32 v4, v8, s69, v94
	v_med3_f32 v5, v9, s69, v94
	v_med3_f32 v6, v12, s69, v94
	v_med3_f32 v7, v13, s69, v94
	v_med3_f32 v8, v24, s69, v94
	v_med3_f32 v24, v25, s69, v94
	v_med3_f32 v9, v30, s69, v94
	v_med3_f32 v25, v31, s69, v94
	ds_read2_b32 v[12:13], v97 offset0:140 offset1:173
	ds_read2_b32 v[30:31], v97 offset0:206 offset1:239
	v_mul_f32_e32 v11, 0x43000000, v11
	s_waitcnt lgkmcnt(3)
	v_mul_f32_e32 v14, 0x43000000, v14
	v_mul_f32_e32 v10, 0x43000000, v10
	v_med3_f32 v21, v11, s69, v94
	v_mul_f32_e32 v11, 0x43000000, v28
	v_med3_f32 v28, v14, s69, v94
	v_mul_f32_e32 v14, 0x43000000, v15
	s_waitcnt lgkmcnt(2)
	v_mul_f32_e32 v15, 0x43000000, v106
	v_mul_f32_e32 v0, 0x43000000, v0
	v_mul_f32_e32 v1, 0x43000000, v1
	v_med3_f32 v20, v10, s69, v94
	v_mul_f32_e32 v10, 0x43000000, v26
	v_med3_f32 v26, v11, s69, v94
	v_mul_f32_e32 v11, 0x43000000, v27
	v_mul_f32_e32 v27, 0x43000000, v29
	s_waitcnt lgkmcnt(1)
	v_mul_f32_e32 v12, 0x43000000, v12
	v_mul_f32_e32 v13, 0x43000000, v13
	v_med3_f32 v29, v14, s69, v94
	s_waitcnt lgkmcnt(0)
; #define LAS __attribute__((address_space(3)))
; #define LDS_WAIT() asm volatile("s_waitcnt lgkmcnt(0)" ::: "memory")
;     __device__ __forceinline__ unsigned a(const pg8::Unit& u) const { return (unsigned)u.pm * (256u * K * 2u); }
;     __device__ __forceinline__ unsigned a(const pg8::Unit& u) const { return (unsigned)u.pm * (256u * K * 2u); }
;     __device__ __forceinline__ unsigned a(const pg8::Unit& u) const { return (unsigned)u.pm * (256u * K * 2u); }
;     __device__ __forceinline__ unsigned a(const pg8::Unit& u) const { return (unsigned)u.pm * (256u * K * 2u); }
;     __device__ __forceinline__ unsigned a(const pg8::Unit& u) const { return (unsigned)u.pm * (256u * K * 2u); }
; __device__ __forceinline__ void p0_transpose_pair_fp6(const float* W, int K, int N, int ncol0, unsigned char* WT6, int row0, LAS float* scr, int kb, int lane) {
;     ...
;     for (int h = 0; h < 2; ++h) {
;         const int k0 = 64 * (kb + h);
; #pragma unroll 8
;         for (int i = 0; i < 8; ++i) { const int kk = 8 * i + (lane >> 3), n4 = (lane & 7) * 4;
;         const f32x4 v4 = *(const f32x4*)(W + (size_t)(k0 + kk) * N + ncol0 + n4); LAS float* d4 = scr + kk * 33 + n4; d4[0] = v4[0]; d4[1] = v4[1]; d4[2] = v4[2]; d4[3] = v4[3]; }
;         LDS_WAIT(); asm volatile("" ::: "memory");
;         f32x16v a, b;
; #pragma unroll
;         for (int i = 0; i < 16; ++i) { a[i] = __builtin_amdgcn_fmed3f(scr[(grp * 32 + i) * 33 + n] * W6_SCALE, -7.5f, 7.5f); b[i] = __builtin_amdgcn_fmed3f(scr[(grp * 32 + 16 + i) * 33 + n] * W6_SCALE, -7.5f, 7.5f); }
;         const u32x6v p = __builtin_amdgcn_cvt_scalef32_2xpk16_fp6_f32(a, b, 1.0f);
;         const int fq = h * 2 + grp;
;         *(LAS u32x4*)(stg + n * 36 + fq * 4) = (u32x4){p[0], p[1], p[2], p[3]};
;         *(LAS u32x4*)(stg + n * 36 + 16 + fq * 4) = (u32x4){p[4], p[5], 0u, 0u};
;         LDS_WAIT(); asm volatile("" ::: "memory");
	v_mul_f32_e32 v14, 0x43000000, v30
	v_med3_f32 v30, v15, s69, v94
	v_mul_f32_e32 v15, 0x43000000, v31
	v_mul_f32_e32 v31, 0x43000000, v107
	v_med3_f32 v0, v0, s69, v94
	v_med3_f32 v1, v1, s69, v94
	v_med3_f32 v10, v10, s69, v94
	v_med3_f32 v11, v11, s69, v94
	v_med3_f32 v27, v27, s69, v94
	v_med3_f32 v12, v12, s69, v94
	v_med3_f32 v13, v13, s69, v94
	v_med3_f32 v14, v14, s69, v94
	v_med3_f32 v15, v15, s69, v94
	v_med3_f32 v31, v31, s69, v94
	v_cvt_scalef32_2xpk16_fp6_f32 v[0:5], v[0:15], v[16:31], 1.0
	ds_write_b128 v120, v[0:3] offset:8448
	v_mov_b32_e32 v0, v4
	v_mov_b32_e32 v1, v5
	v_mov_b32_e32 v2, v33
	v_mov_b32_e32 v3, v33
	ds_write_b64 v122, v[0:1] offset:8512
	s_waitcnt lgkmcnt(0)
	v_or_b32_e32 v0, s0, v64
	v_or_b32_e32 v2, s0, v65
	v_or_b32_e32 v8, s0, v67
	v_or_b32_e32 v10, s0, v69
	v_or_b32_e32 v16, s0, v70
	v_or_b32_e32 v18, s0, v71
	v_mad_i64_i32 v[0:1], s[66:67], v0, s68, v[62:63]
	v_mad_i64_i32 v[4:5], s[66:67], v2, s68, v[62:63]
	v_mad_i64_i32 v[8:9], s[66:67], v8, s68, v[62:63]
	v_mad_i64_i32 v[12:13], s[66:67], v10, s68, v[62:63]
	v_mad_i64_i32 v[16:17], s[66:67], v16, s68, v[62:63]
	v_mad_i64_i32 v[20:21], s[66:67], v18, s68, v[62:63]
	global_load_dwordx4 v[0:3], v[0:1], off
	s_nop 0
	global_load_dwordx4 v[4:7], v[4:5], off
	s_nop 0
	global_load_dwordx4 v[8:11], v[8:9], off
	s_nop 0
	global_load_dwordx4 v[12:15], v[12:13], off
	s_nop 0
	global_load_dwordx4 v[16:19], v[16:17], off
	s_nop 0
	global_load_dwordx4 v[20:23], v[20:21], off
	v_or_b32_e32 v24, s0, v72
	v_mad_i64_i32 v[24:25], s[66:67], v24, s68, v[62:63]
	global_load_dwordx4 v[24:27], v[24:25], off
	v_or_b32_e32 v28, s0, v73
	v_mad_i64_i32 v[28:29], s[66:67], v28, s68, v[62:63]
	global_load_dwordx4 v[28:31], v[28:29], off
	s_waitcnt vmcnt(7)
	ds_write2_b32 v37, v0, v1 offset1:1
	ds_write2_b32 v37, v2, v3 offset0:2 offset1:3
	s_waitcnt vmcnt(6)
	ds_write2_b32 v79, v4, v5 offset1:1
	ds_write2_b32 v80, v6, v7 offset1:1
	s_waitcnt vmcnt(5)
	ds_write2_b32 v81, v8, v9 offset1:1
	ds_write2_b32 v82, v10, v11 offset1:1
	s_waitcnt vmcnt(4)
	ds_write2_b32 v83, v12, v13 offset1:1
	ds_write2_b32 v84, v14, v15 offset1:1
	s_waitcnt vmcnt(3)
	ds_write2_b32 v85, v16, v17 offset1:1
	ds_write2_b32 v86, v18, v19 offset1:1
	s_waitcnt vmcnt(2)
	ds_write2_b32 v87, v20, v21 offset1:1
	ds_write2_b32 v88, v22, v23 offset1:1
	s_waitcnt vmcnt(1)
	ds_write2_b32 v89, v24, v25 offset1:1
	ds_write2_b32 v90, v26, v27 offset1:1
	s_waitcnt vmcnt(0)
	ds_write2_b32 v91, v28, v29 offset1:1
	ds_write2_b32 v92, v30, v31 offset1:1
	s_waitcnt lgkmcnt(0)
	ds_read2_b32 v[0:1], v75 offset1:33
	ds_read2_b32 v[2:3], v98 offset0:16 offset1:49
	ds_read2_b32 v[6:7], v98 offset0:82 offset1:115
	ds_read2_b32 v[8:9], v98 offset0:148 offset1:181
	ds_read2_b32 v[10:11], v98 offset0:214 offset1:247
	ds_read2_b32 v[12:13], v96 offset0:24 offset1:57
	s_waitcnt lgkmcnt(4)
	v_mul_f32_e32 v2, 0x43000000, v2
	ds_read2_b32 v[14:15], v96 offset0:90 offset1:123
	v_med3_f32 v16, v2, s69, v94
	v_mul_f32_e32 v2, 0x43000000, v3
	s_waitcnt lgkmcnt(4)
	v_mul_f32_e32 v3, 0x43000000, v6
	v_mul_f32_e32 v6, 0x43000000, v7
	ds_read2_b32 v[28:29], v96 offset0:156 offset1:189
	ds_read2_b32 v[4:5], v75 offset0:66 offset1:99
	v_med3_f32 v19, v6, s69, v94
	s_waitcnt lgkmcnt(5)
	v_mul_f32_e32 v6, 0x43000000, v8
	v_mul_f32_e32 v8, 0x43000000, v9
	v_med3_f32 v21, v8, s69, v94
	s_waitcnt lgkmcnt(4)
	v_mul_f32_e32 v8, 0x43000000, v10
	v_mul_f32_e32 v10, 0x43000000, v11
	v_med3_f32 v23, v10, s69, v94
	s_waitcnt lgkmcnt(3)
	v_mul_f32_e32 v10, 0x43000000, v12
	v_mul_f32_e32 v12, 0x43000000, v13
	v_med3_f32 v25, v12, s69, v94
	s_waitcnt lgkmcnt(2)
	v_mul_f32_e32 v12, 0x43000000, v14
	v_mul_f32_e32 v14, 0x43000000, v15
	v_med3_f32 v27, v14, s69, v94
	s_waitcnt lgkmcnt(1)
	v_mul_f32_e32 v14, 0x43000000, v28
	v_med3_f32 v17, v2, s69, v94
	s_waitcnt lgkmcnt(0)
	v_mul_f32_e32 v2, 0x43000000, v4
	v_med3_f32 v18, v3, s69, v94
	v_mul_f32_e32 v3, 0x43000000, v5
	ds_read2_b32 v[4:5], v75 offset0:132 offset1:165
	v_med3_f32 v20, v6, s69, v94
	ds_read2_b32 v[6:7], v75 offset0:198 offset1:231
	v_med3_f32 v22, v8, s69, v94
	ds_read2_b32 v[8:9], v97 offset0:8 offset1:41
	v_med3_f32 v24, v10, s69, v94
	ds_read2_b32 v[10:11], v97 offset0:74 offset1:107
	v_med3_f32 v26, v12, s69, v94
	ds_read2_b32 v[12:13], v97 offset0:140 offset1:173
	v_med3_f32 v28, v14, s69, v94
	ds_read2_b32 v[14:15], v97 offset0:206 offset1:239
	ds_read2_b32 v[30:31], v96 offset0:222 offset1:255
	v_mul_f32_e32 v0, 0x43000000, v0
	v_mul_f32_e32 v1, 0x43000000, v1
	s_waitcnt lgkmcnt(6)
	v_mul_f32_e32 v4, 0x43000000, v4
	v_mul_f32_e32 v5, 0x43000000, v5
	s_waitcnt lgkmcnt(5)
	v_mul_f32_e32 v6, 0x43000000, v6
	v_mul_f32_e32 v7, 0x43000000, v7
	s_waitcnt lgkmcnt(4)
	v_mul_f32_e32 v8, 0x43000000, v8
	v_mul_f32_e32 v9, 0x43000000, v9
	s_waitcnt lgkmcnt(3)
	v_mul_f32_e32 v10, 0x43000000, v10
	v_mul_f32_e32 v11, 0x43000000, v11
	s_waitcnt lgkmcnt(2)
	v_mul_f32_e32 v12, 0x43000000, v12
	v_mul_f32_e32 v13, 0x43000000, v13
	v_mul_f32_e32 v29, 0x43000000, v29
	s_waitcnt lgkmcnt(1)
	v_mul_f32_e32 v14, 0x43000000, v14
	s_waitcnt lgkmcnt(0)
	v_mul_f32_e32 v30, 0x43000000, v30
	v_mul_f32_e32 v15, 0x43000000, v15
	v_mul_f32_e32 v31, 0x43000000, v31
	v_med3_f32 v0, v0, s69, v94
	v_med3_f32 v1, v1, s69, v94
	v_med3_f32 v2, v2, s69, v94
	v_med3_f32 v3, v3, s69, v94
	v_med3_f32 v4, v4, s69, v94
	v_med3_f32 v5, v5, s69, v94
	v_med3_f32 v6, v6, s69, v94
	v_med3_f32 v7, v7, s69, v94
	v_med3_f32 v8, v8, s69, v94
	v_med3_f32 v9, v9, s69, v94
	v_med3_f32 v10, v10, s69, v94
	v_med3_f32 v11, v11, s69, v94
	v_med3_f32 v12, v12, s69, v94
	v_med3_f32 v13, v13, s69, v94
	v_med3_f32 v29, v29, s69, v94
	v_med3_f32 v14, v14, s69, v94
	v_med3_f32 v30, v30, s69, v94
	v_med3_f32 v15, v15, s69, v94
	v_med3_f32 v31, v31, s69, v94
	v_cvt_scalef32_2xpk16_fp6_f32 v[0:5], v[0:15], v[16:31], 1.0
	ds_write_b128 v121, v[0:3] offset:8480
	v_mov_b32_e32 v0, v4
	v_mov_b32_e32 v1, v5
	v_mov_b32_e32 v2, v33
	v_mov_b32_e32 v3, v33
	ds_write_b64 v123, v[0:1] offset:8512
	s_waitcnt lgkmcnt(0)
; #define LAS __attribute__((address_space(3)))
; #define LDS_WAIT() asm volatile("s_waitcnt lgkmcnt(0)" ::: "memory")
;     __device__ __forceinline__ unsigned a(const pg8::Unit& u) const { return (unsigned)u.pm * (256u * K * 2u); }
;     __device__ __forceinline__ unsigned a(const pg8::Unit& u) const { return (unsigned)u.pm * (256u * K * 2u); }
;     __device__ __forceinline__ unsigned a(const pg8::Unit& u) const { return (unsigned)u.pm * (256u * K * 2u); }
;     __device__ __forceinline__ unsigned a(const pg8::Unit& u) const { return (unsigned)u.pm * (256u * K * 2u); }
;     __device__ __forceinline__ unsigned a(const pg8::Unit& u) const { return (unsigned)u.pm * (256u * K * 2u); }
; __device__ __forceinline__ void p0_transpose_pair_fp6(const float* W, int K, int N, int ncol0, unsigned char* WT6, int row0, LAS float* scr, int kb, int lane) {
;     ...
;         for (int i = 0; i < 8; ++i) { const int kk = 8 * i + (lane >> 3), n4 = (lane & 7) * 4;
;         const f32x4 v4 = *(const f32x4*)(W + (size_t)(k0 + kk) * N + ncol0 + n4); LAS float* d4 = scr + kk * 33 + n4; d4[0] = v4[0]; d4[1] = v4[1]; d4[2] = v4[2]; d4[3] = v4[3]; }
;         LDS_WAIT(); asm volatile("" ::: "memory");
;         f32x16v a, b;
; #pragma unroll
;         for (int i = 0; i < 16; ++i) { a[i] = __builtin_amdgcn_fmed3f(scr[(grp * 32 + i) * 33 + n] * W6_SCALE, -7.5f, 7.5f); b[i] = __builtin_amdgcn_fmed3f(scr[(grp * 32 + 16 + i) * 33 + n] * W6_SCALE, -7.5f, 7.5f); }
;     ...
; #pragma unroll
;     for (int j = 0; j < 4; ++j) { const int q = j * 64 + lane;
;         const u32x4 t = *(const LAS u32x4*)(stg + (q >> 3) * 36 + (q & 7) * 4);
;         *(u32x4*)(WT6 + (size_t)(row0 + (q >> 3)) * K + (kb >> 1) * 128 + (q & 7) * 16) = t; }
;     LDS_WAIT(); asm volatile("" ::: "memory");
	ds_read_b128 v[0:3], v124 offset:8448
	v_lshl_add_u64 v[8:9], v[54:55], 0, s[58:59]
	v_lshlrev_b64 v[4:5], 12, v[56:57]
	v_lshl_add_u64 v[10:11], v[8:9], 0, v[4:5]
	v_bfe_u32 v126, v56, 6, 1
	v_bfe_u32 v117, v66, 3, 1
	v_and_b32_e32 v117, v117, v126
	v_mul_u32_u24_e32 v117, 0xfc0, v117
	v_sub_u32_e32 v117, 0, v117
	v_mul_u32_u24_e32 v127, 0x3ffe0, v126
	v_sub_u32_e32 v127, 0, v127
	v_sub_u32_e32 v127, v127, v125
	v_bfe_i32 v116, v66, 2, 1
	v_bfi_b32 v118, v116, v127, v117
	v_ashrrev_i32_e32 v119, 31, v118
	v_lshlrev_b32_e32 v126, 6, v126
	v_sub_u32_e32 v126, 32, v126
	v_add_u32_e32 v126, v127, v126
	v_bfi_b32 v116, v116, v126, v117
	v_ashrrev_i32_e32 v117, 31, v116
	v_lshl_add_u64 v[10:11], v[10:11], 0, v[118:119]
	ds_read_b128 v[4:7], v124 offset:9600
	s_waitcnt lgkmcnt(1)
	global_store_dwordx4 v[10:11], v[0:3], off
	s_mov_b64 s[66:67], 0
	s_nop 0
	v_add_u32_e32 v0, 8, v56
	v_mov_b32_e32 v1, v33
	v_lshlrev_b64 v[0:1], 12, v[0:1]
	v_lshl_add_u64 v[0:1], v[8:9], 0, v[0:1]
	v_lshl_add_u64 v[0:1], v[0:1], 0, v[116:117]
	s_waitcnt lgkmcnt(0)
	global_store_dwordx4 v[0:1], v[4:7], off
	ds_read_b128 v[0:3], v124 offset:10752
	s_nop 0
	v_add_u32_e32 v4, 16, v56
	v_mov_b32_e32 v5, v33
	v_lshlrev_b64 v[4:5], 12, v[4:5]
	v_lshl_add_u64 v[10:11], v[8:9], 0, v[4:5]
	v_lshl_add_u64 v[10:11], v[10:11], 0, v[118:119]
	ds_read_b128 v[4:7], v124 offset:11904
	s_waitcnt lgkmcnt(1)
	global_store_dwordx4 v[10:11], v[0:3], off
	s_nop 1
	v_add_u32_e32 v0, 24, v56
	v_mov_b32_e32 v1, v33
	v_lshlrev_b64 v[0:1], 12, v[0:1]
	v_lshl_add_u64 v[0:1], v[8:9], 0, v[0:1]
	v_lshl_add_u64 v[0:1], v[0:1], 0, v[116:117]
	s_waitcnt lgkmcnt(0)
	global_store_dwordx4 v[0:1], v[4:7], off
	s_waitcnt lgkmcnt(0)
.LBB0_47:
	s_andn2_b64 vcc, exec, s[66:67]
	s_cbranch_vccnz .LBB0_14
	s_ashr_i32 s63, s62, 31
	s_lshl_b64 s[62:63], s[62:63], 2
	s_add_u32 s62, s16, s62
	s_addc_u32 s63, s17, s63
	v_lshl_add_u64 v[0:1], s[62:63], 0, v[32:33]
	v_lshl_add_u64 v[62:63], v[0:1], 0, s[8:9]
	v_lshl_add_u64 v[0:1], v[62:63], 0, v[60:61]
	v_lshl_add_u64 v[4:5], v[62:63], 0, v[58:59]
	v_mad_i64_i32 v[8:9], s[62:63], v104, s68, v[62:63]
	v_mad_i64_i32 v[12:13], s[62:63], v103, s68, v[62:63]
	v_mad_i64_i32 v[16:17], s[62:63], v102, s68, v[62:63]
	v_mad_i64_i32 v[20:21], s[62:63], v101, s68, v[62:63]
	v_mad_i64_i32 v[24:25], s[62:63], v100, s68, v[62:63]
	global_load_dwordx4 v[0:3], v[0:1], off
	s_nop 0
	global_load_dwordx4 v[4:7], v[4:5], off
	s_nop 0
	global_load_dwordx4 v[8:11], v[8:9], off
	s_nop 0
	global_load_dwordx4 v[12:15], v[12:13], off
	s_nop 0
	global_load_dwordx4 v[16:19], v[16:17], off
	s_nop 0
	global_load_dwordx4 v[20:23], v[20:21], off
	s_nop 0
	global_load_dwordx4 v[24:27], v[24:25], off
	v_mad_i64_i32 v[28:29], s[62:63], v99, s68, v[62:63]
	global_load_dwordx4 v[28:31], v[28:29], off
	v_mov_b32_e32 v32, v33
	s_or_b32 s0, s58, 64
	s_ashr_i32 s59, s58, 31
	v_ashrrev_i32_e32 v57, 31, v56
	s_waitcnt vmcnt(7)
	ds_write2_b32 v37, v0, v1 offset1:1
	ds_write2_b32 v37, v2, v3 offset0:2 offset1:3
	s_waitcnt vmcnt(6)
	ds_write2_b32 v79, v4, v5 offset1:1
	ds_write2_b32 v80, v6, v7 offset1:1
	s_waitcnt vmcnt(5)
	ds_write2_b32 v81, v8, v9 offset1:1
	ds_write2_b32 v82, v10, v11 offset1:1
	s_waitcnt vmcnt(4)
	ds_write2_b32 v83, v12, v13 offset1:1
	ds_write2_b32 v84, v14, v15 offset1:1
	s_waitcnt vmcnt(3)
	ds_write2_b32 v85, v16, v17 offset1:1
	ds_write2_b32 v86, v18, v19 offset1:1
	s_waitcnt vmcnt(2)
	ds_write2_b32 v87, v20, v21 offset1:1
	ds_write2_b32 v88, v22, v23 offset1:1
	s_waitcnt vmcnt(1)
	ds_write2_b32 v89, v24, v25 offset1:1
	ds_write2_b32 v90, v26, v27 offset1:1
	s_waitcnt vmcnt(0)
	ds_write2_b32 v91, v28, v29 offset1:1
	ds_write2_b32 v92, v30, v31 offset1:1
	s_waitcnt lgkmcnt(0)
	ds_read2_b32 v[0:1], v75 offset1:33
	ds_read2_b32 v[2:3], v98 offset0:16 offset1:49
	ds_read2_b32 v[4:5], v75 offset0:66 offset1:99
	ds_read2_b32 v[6:7], v98 offset0:82 offset1:115
	ds_read2_b32 v[8:9], v75 offset0:132 offset1:165
	ds_read2_b32 v[10:11], v98 offset0:148 offset1:181
	ds_read2_b32 v[12:13], v75 offset0:198 offset1:231
	ds_read2_b32 v[14:15], v98 offset0:214 offset1:247
	ds_read2_b32 v[16:17], v97 offset0:8 offset1:41
	ds_read2_b32 v[18:19], v96 offset0:24 offset1:57
	ds_read2_b32 v[26:27], v97 offset0:74 offset1:107
	ds_read2_b32 v[28:29], v96 offset0:90 offset1:123
	s_waitcnt lgkmcnt(4)
	v_mul_f32_e32 v14, 0x43000000, v14
	v_mul_f32_e32 v15, 0x43000000, v15
	v_med3_f32 v22, v14, s69, v94
	v_med3_f32 v23, v15, s69, v94
	ds_read2_b32 v[14:15], v96 offset0:156 offset1:189
	v_mul_f32_e32 v2, 0x43000000, v2
	v_mul_f32_e32 v3, 0x43000000, v3
	v_mul_f32_e32 v4, 0x43000000, v4
	v_mul_f32_e32 v6, 0x43000000, v6
	v_mul_f32_e32 v5, 0x43000000, v5
	v_mul_f32_e32 v7, 0x43000000, v7
	v_mul_f32_e32 v8, 0x43000000, v8
	v_mul_f32_e32 v9, 0x43000000, v9
	v_mul_f32_e32 v12, 0x43000000, v12
	v_mul_f32_e32 v13, 0x43000000, v13
	s_waitcnt lgkmcnt(4)
	v_mul_f32_e32 v24, 0x43000000, v16
	s_waitcnt lgkmcnt(3)
	v_mul_f32_e32 v25, 0x43000000, v18
	v_mul_f32_e32 v30, 0x43000000, v17
	v_mul_f32_e32 v31, 0x43000000, v19
	ds_read2_b32 v[58:59], v96 offset0:222 offset1:255
	v_med3_f32 v16, v2, s69, v94
	v_med3_f32 v17, v3, s69, v94
	v_med3_f32 v2, v4, s69, v94
	v_med3_f32 v18, v6, s69, v94
	v_med3_f32 v3, v5, s69, v94
	v_med3_f32 v19, v7, s69, v94
	v_med3_f32 v4, v8, s69, v94
	v_med3_f32 v5, v9, s69, v94
	v_med3_f32 v6, v12, s69, v94
	v_med3_f32 v7, v13, s69, v94
	v_med3_f32 v8, v24, s69, v94
	v_med3_f32 v24, v25, s69, v94
	v_med3_f32 v9, v30, s69, v94
	v_med3_f32 v25, v31, s69, v94
	ds_read2_b32 v[12:13], v97 offset0:140 offset1:173
	ds_read2_b32 v[30:31], v97 offset0:206 offset1:239
	v_mul_f32_e32 v11, 0x43000000, v11
	s_waitcnt lgkmcnt(3)
; #define LAS __attribute__((address_space(3)))
; #define LDS_WAIT() asm volatile("s_waitcnt lgkmcnt(0)" ::: "memory")
;     __device__ __forceinline__ unsigned a(const pg8::Unit& u) const { return (unsigned)u.pm * (256u * K * 2u); }
;     __device__ __forceinline__ unsigned a(const pg8::Unit& u) const { return (unsigned)u.pm * (256u * K * 2u); }
;     __device__ __forceinline__ unsigned a(const pg8::Unit& u) const { return (unsigned)u.pm * (256u * K * 2u); }
;     __device__ __forceinline__ unsigned a(const pg8::Unit& u) const { return (unsigned)u.pm * (256u * K * 2u); }
;     __device__ __forceinline__ unsigned a(const pg8::Unit& u) const { return (unsigned)u.pm * (256u * K * 2u); }
; __device__ __forceinline__ void p0_transpose_pair_fp6(const float* W, int K, int N, int ncol0, unsigned char* WT6, int row0, LAS float* scr, int kb, int lane) {
;     ...
;     for (int h = 0; h < 2; ++h) {
;         const int k0 = 64 * (kb + h);
; #pragma unroll 8
;         for (int i = 0; i < 8; ++i) { const int kk = 8 * i + (lane >> 3), n4 = (lane & 7) * 4;
;         const f32x4 v4 = *(const f32x4*)(W + (size_t)(k0 + kk) * N + ncol0 + n4); LAS float* d4 = scr + kk * 33 + n4; d4[0] = v4[0]; d4[1] = v4[1]; d4[2] = v4[2]; d4[3] = v4[3]; }
;         LDS_WAIT(); asm volatile("" ::: "memory");
;         f32x16v a, b;
; #pragma unroll
;         for (int i = 0; i < 16; ++i) { a[i] = __builtin_amdgcn_fmed3f(scr[(grp * 32 + i) * 33 + n] * W6_SCALE, -7.5f, 7.5f); b[i] = __builtin_amdgcn_fmed3f(scr[(grp * 32 + 16 + i) * 33 + n] * W6_SCALE, -7.5f, 7.5f); }
;         const u32x6v p = __builtin_amdgcn_cvt_scalef32_2xpk16_fp6_f32(a, b, 1.0f);
;         const int fq = h * 2 + grp;
;         *(LAS u32x4*)(stg + n * 36 + fq * 4) = (u32x4){p[0], p[1], p[2], p[3]};
;         *(LAS u32x4*)(stg + n * 36 + 16 + fq * 4) = (u32x4){p[4], p[5], 0u, 0u};
;         LDS_WAIT(); asm volatile("" ::: "memory");
	v_mul_f32_e32 v14, 0x43000000, v14
	v_mul_f32_e32 v10, 0x43000000, v10
	v_med3_f32 v21, v11, s69, v94
	v_mul_f32_e32 v11, 0x43000000, v28
	v_med3_f32 v28, v14, s69, v94
	v_mul_f32_e32 v14, 0x43000000, v15
	s_waitcnt lgkmcnt(2)
	v_mul_f32_e32 v15, 0x43000000, v58
	v_mul_f32_e32 v0, 0x43000000, v0
	v_mul_f32_e32 v1, 0x43000000, v1
	v_med3_f32 v20, v10, s69, v94
	v_mul_f32_e32 v10, 0x43000000, v26
	v_med3_f32 v26, v11, s69, v94
	v_mul_f32_e32 v11, 0x43000000, v27
	v_mul_f32_e32 v27, 0x43000000, v29
	s_waitcnt lgkmcnt(1)
	v_mul_f32_e32 v12, 0x43000000, v12
	v_mul_f32_e32 v13, 0x43000000, v13
	v_med3_f32 v29, v14, s69, v94
	s_waitcnt lgkmcnt(0)
	v_mul_f32_e32 v14, 0x43000000, v30
	v_med3_f32 v30, v15, s69, v94
	v_mul_f32_e32 v15, 0x43000000, v31
	v_mul_f32_e32 v31, 0x43000000, v59
	v_med3_f32 v0, v0, s69, v94
	v_med3_f32 v1, v1, s69, v94
	v_med3_f32 v10, v10, s69, v94
	v_med3_f32 v11, v11, s69, v94
	v_med3_f32 v27, v27, s69, v94
	v_med3_f32 v12, v12, s69, v94
	v_med3_f32 v13, v13, s69, v94
	v_med3_f32 v14, v14, s69, v94
	v_med3_f32 v15, v15, s69, v94
	v_med3_f32 v31, v31, s69, v94
	v_cvt_scalef32_2xpk16_fp6_f32 v[0:5], v[0:15], v[16:31], 1.0
	v_mov_b32_e32 v30, v4
	v_mov_b32_e32 v31, v5
	ds_write_b128 v120, v[0:3] offset:8448
	ds_write_b64 v122, v[30:31] offset:8512
	s_waitcnt lgkmcnt(0)
	v_or_b32_e32 v0, s0, v64
	v_or_b32_e32 v4, s0, v65
	v_or_b32_e32 v6, s0, v67
	v_or_b32_e32 v7, s0, v69
	v_or_b32_e32 v10, s0, v70
	v_or_b32_e32 v14, s0, v71
	v_or_b32_e32 v22, s0, v72
	v_mad_i64_i32 v[0:1], s[62:63], v0, s68, v[62:63]
	v_mad_i64_i32 v[4:5], s[62:63], v4, s68, v[62:63]
	v_mad_i64_i32 v[8:9], s[62:63], v6, s68, v[62:63]
	v_mad_i64_i32 v[12:13], s[62:63], v7, s68, v[62:63]
	v_mad_i64_i32 v[16:17], s[62:63], v10, s68, v[62:63]
	v_mad_i64_i32 v[20:21], s[62:63], v14, s68, v[62:63]
	v_mad_i64_i32 v[24:25], s[62:63], v22, s68, v[62:63]
	global_load_dwordx4 v[0:3], v[0:1], off
	s_nop 0
	global_load_dwordx4 v[4:7], v[4:5], off
	s_nop 0
	global_load_dwordx4 v[8:11], v[8:9], off
	s_nop 0
	global_load_dwordx4 v[12:15], v[12:13], off
	s_nop 0
	global_load_dwordx4 v[16:19], v[16:17], off
	s_nop 0
	global_load_dwordx4 v[20:23], v[20:21], off
	s_nop 0
	global_load_dwordx4 v[24:27], v[24:25], off
	v_or_b32_e32 v28, s0, v73
	v_mad_i64_i32 v[28:29], s[62:63], v28, s68, v[62:63]
	global_load_dwordx4 v[28:31], v[28:29], off
	s_waitcnt vmcnt(7)
	ds_write2_b32 v37, v0, v1 offset1:1
	ds_write2_b32 v37, v2, v3 offset0:2 offset1:3
	s_waitcnt vmcnt(6)
	ds_write2_b32 v79, v4, v5 offset1:1
	ds_write2_b32 v80, v6, v7 offset1:1
	s_waitcnt vmcnt(5)
	ds_write2_b32 v81, v8, v9 offset1:1
	ds_write2_b32 v82, v10, v11 offset1:1
	s_waitcnt vmcnt(4)
	ds_write2_b32 v83, v12, v13 offset1:1
	ds_write2_b32 v84, v14, v15 offset1:1
	s_waitcnt vmcnt(3)
	ds_write2_b32 v85, v16, v17 offset1:1
	ds_write2_b32 v86, v18, v19 offset1:1
	s_waitcnt vmcnt(2)
	ds_write2_b32 v87, v20, v21 offset1:1
	ds_write2_b32 v88, v22, v23 offset1:1
	s_waitcnt vmcnt(1)
	ds_write2_b32 v89, v24, v25 offset1:1
	ds_write2_b32 v90, v26, v27 offset1:1
	s_waitcnt vmcnt(0)
	ds_write2_b32 v91, v28, v29 offset1:1
	ds_write2_b32 v92, v30, v31 offset1:1
	s_waitcnt lgkmcnt(0)
	ds_read2_b32 v[0:1], v75 offset1:33
	ds_read2_b32 v[2:3], v98 offset0:16 offset1:49
	ds_read2_b32 v[6:7], v98 offset0:82 offset1:115
	ds_read2_b32 v[8:9], v98 offset0:148 offset1:181
	ds_read2_b32 v[10:11], v98 offset0:214 offset1:247
	ds_read2_b32 v[12:13], v96 offset0:24 offset1:57
	s_waitcnt lgkmcnt(4)
	v_mul_f32_e32 v3, 0x43000000, v3
	ds_read2_b32 v[14:15], v96 offset0:90 offset1:123
	v_med3_f32 v17, v3, s69, v94
	s_waitcnt lgkmcnt(4)
	v_mul_f32_e32 v3, 0x43000000, v6
	v_mul_f32_e32 v6, 0x43000000, v7
	ds_read2_b32 v[28:29], v96 offset0:156 offset1:189
	ds_read2_b32 v[4:5], v75 offset0:66 offset1:99
	v_med3_f32 v19, v6, s69, v94
	s_waitcnt lgkmcnt(5)
	v_mul_f32_e32 v6, 0x43000000, v8
	v_mul_f32_e32 v8, 0x43000000, v9
	v_med3_f32 v21, v8, s69, v94
	s_waitcnt lgkmcnt(4)
	v_mul_f32_e32 v8, 0x43000000, v10
	v_mul_f32_e32 v10, 0x43000000, v11
	v_med3_f32 v23, v10, s69, v94
	s_waitcnt lgkmcnt(3)
	v_mul_f32_e32 v10, 0x43000000, v12
	v_mul_f32_e32 v12, 0x43000000, v13
	v_med3_f32 v25, v12, s69, v94
	s_waitcnt lgkmcnt(2)
; #define LAS __attribute__((address_space(3)))
; #define LDS_WAIT() asm volatile("s_waitcnt lgkmcnt(0)" ::: "memory")
;     __device__ __forceinline__ unsigned a(const pg8::Unit& u) const { return (unsigned)u.pm * (256u * K * 2u); }
;     __device__ __forceinline__ unsigned a(const pg8::Unit& u) const { return (unsigned)u.pm * (256u * K * 2u); }
;     __device__ __forceinline__ unsigned a(const pg8::Unit& u) const { return (unsigned)u.pm * (256u * K * 2u); }
;     __device__ __forceinline__ unsigned a(const pg8::Unit& u) const { return (unsigned)u.pm * (256u * K * 2u); }
;     __device__ __forceinline__ unsigned a(const pg8::Unit& u) const { return (unsigned)u.pm * (256u * K * 2u); }
; __device__ __forceinline__ void p0_transpose_pair_fp6(const float* W, int K, int N, int ncol0, unsigned char* WT6, int row0, LAS float* scr, int kb, int lane) {
;     ...
;         for (int i = 0; i < 16; ++i) { a[i] = __builtin_amdgcn_fmed3f(scr[(grp * 32 + i) * 33 + n] * W6_SCALE, -7.5f, 7.5f); b[i] = __builtin_amdgcn_fmed3f(scr[(grp * 32 + 16 + i) * 33 + n] * W6_SCALE, -7.5f, 7.5f); }
;         const u32x6v p = __builtin_amdgcn_cvt_scalef32_2xpk16_fp6_f32(a, b, 1.0f);
;         const int fq = h * 2 + grp;
;         *(LAS u32x4*)(stg + n * 36 + fq * 4) = (u32x4){p[0], p[1], p[2], p[3]};
;         *(LAS u32x4*)(stg + n * 36 + 16 + fq * 4) = (u32x4){p[4], p[5], 0u, 0u};
;         LDS_WAIT(); asm volatile("" ::: "memory");
;     }
; #pragma unroll
;     for (int j = 0; j < 4; ++j) { const int q = j * 64 + lane;
;         const u32x4 t = *(const LAS u32x4*)(stg + (q >> 3) * 36 + (q & 7) * 4);
;         *(u32x4*)(WT6 + (size_t)(row0 + (q >> 3)) * K + (kb >> 1) * 128 + (q & 7) * 16) = t; }
;     LDS_WAIT(); asm volatile("" ::: "memory");
	v_mul_f32_e32 v12, 0x43000000, v14
	v_mul_f32_e32 v14, 0x43000000, v15
	v_mul_f32_e32 v2, 0x43000000, v2
	v_med3_f32 v27, v14, s69, v94
	s_waitcnt lgkmcnt(1)
	v_mul_f32_e32 v14, 0x43000000, v28
	v_med3_f32 v16, v2, s69, v94
	s_waitcnt lgkmcnt(0)
	v_mul_f32_e32 v2, 0x43000000, v4
	v_med3_f32 v18, v3, s69, v94
	v_mul_f32_e32 v3, 0x43000000, v5
	ds_read2_b32 v[4:5], v75 offset0:132 offset1:165
	v_med3_f32 v20, v6, s69, v94
	ds_read2_b32 v[6:7], v75 offset0:198 offset1:231
	v_med3_f32 v22, v8, s69, v94
	ds_read2_b32 v[8:9], v97 offset0:8 offset1:41
	v_med3_f32 v24, v10, s69, v94
	ds_read2_b32 v[10:11], v97 offset0:74 offset1:107
	v_med3_f32 v26, v12, s69, v94
	ds_read2_b32 v[12:13], v97 offset0:140 offset1:173
	v_med3_f32 v28, v14, s69, v94
	ds_read2_b32 v[14:15], v97 offset0:206 offset1:239
	ds_read2_b32 v[30:31], v96 offset0:222 offset1:255
	v_mul_f32_e32 v0, 0x43000000, v0
	v_mul_f32_e32 v1, 0x43000000, v1
	s_waitcnt lgkmcnt(6)
	v_mul_f32_e32 v4, 0x43000000, v4
	v_mul_f32_e32 v5, 0x43000000, v5
	s_waitcnt lgkmcnt(5)
	v_mul_f32_e32 v6, 0x43000000, v6
	v_mul_f32_e32 v7, 0x43000000, v7
	s_waitcnt lgkmcnt(4)
	v_mul_f32_e32 v8, 0x43000000, v8
	v_mul_f32_e32 v9, 0x43000000, v9
	s_waitcnt lgkmcnt(3)
	v_mul_f32_e32 v10, 0x43000000, v10
	v_mul_f32_e32 v11, 0x43000000, v11
	s_waitcnt lgkmcnt(2)
	v_mul_f32_e32 v12, 0x43000000, v12
	v_mul_f32_e32 v13, 0x43000000, v13
	v_mul_f32_e32 v29, 0x43000000, v29
	s_waitcnt lgkmcnt(1)
	v_mul_f32_e32 v14, 0x43000000, v14
	s_waitcnt lgkmcnt(0)
	v_mul_f32_e32 v30, 0x43000000, v30
	v_mul_f32_e32 v15, 0x43000000, v15
	v_mul_f32_e32 v31, 0x43000000, v31
	v_med3_f32 v0, v0, s69, v94
	v_med3_f32 v1, v1, s69, v94
	v_med3_f32 v2, v2, s69, v94
	v_med3_f32 v3, v3, s69, v94
	v_med3_f32 v4, v4, s69, v94
	v_med3_f32 v5, v5, s69, v94
	v_med3_f32 v6, v6, s69, v94
	v_med3_f32 v7, v7, s69, v94
	v_med3_f32 v8, v8, s69, v94
	v_med3_f32 v9, v9, s69, v94
	v_med3_f32 v10, v10, s69, v94
	v_med3_f32 v11, v11, s69, v94
	v_med3_f32 v12, v12, s69, v94
	v_med3_f32 v13, v13, s69, v94
	v_med3_f32 v29, v29, s69, v94
	v_med3_f32 v14, v14, s69, v94
	v_med3_f32 v30, v30, s69, v94
	v_med3_f32 v15, v15, s69, v94
	v_med3_f32 v31, v31, s69, v94
	v_cvt_scalef32_2xpk16_fp6_f32 v[0:5], v[0:15], v[16:31], 1.0
	v_mov_b32_e32 v30, v4
	v_mov_b32_e32 v31, v5
	ds_write_b128 v121, v[0:3] offset:8480
	ds_write_b64 v123, v[30:31] offset:8512
	s_waitcnt lgkmcnt(0)
	ds_read_b128 v[0:3], v124 offset:8448
	v_lshl_add_u64 v[8:9], v[54:55], 0, s[58:59]
	v_lshlrev_b64 v[4:5], 12, v[56:57]
	v_lshl_add_u64 v[10:11], v[8:9], 0, v[4:5]
	v_bfe_u32 v126, v56, 6, 1
	v_bfe_u32 v117, v66, 3, 1
	v_and_b32_e32 v117, v117, v126
	v_mul_u32_u24_e32 v117, 0xfc0, v117
	v_sub_u32_e32 v117, 0, v117
	v_mul_u32_u24_e32 v127, 0x3ffe0, v126
	v_sub_u32_e32 v127, 0, v127
	v_sub_u32_e32 v127, v127, v125
	v_bfe_i32 v116, v66, 2, 1
	v_bfi_b32 v118, v116, v127, v117
	v_ashrrev_i32_e32 v119, 31, v118
	v_lshlrev_b32_e32 v126, 6, v126
	v_sub_u32_e32 v126, 32, v126
	v_add_u32_e32 v126, v127, v126
	v_bfi_b32 v116, v116, v126, v117
	v_ashrrev_i32_e32 v117, 31, v116
	v_lshl_add_u64 v[10:11], v[10:11], 0, v[118:119]
	ds_read_b128 v[4:7], v124 offset:9600
	s_waitcnt lgkmcnt(1)
	global_store_dwordx4 v[10:11], v[0:3], off
	s_nop 1
	v_add_u32_e32 v0, 8, v56
	v_ashrrev_i32_e32 v1, 31, v0
	v_lshlrev_b64 v[0:1], 12, v[0:1]
	v_lshl_add_u64 v[0:1], v[8:9], 0, v[0:1]
	v_lshl_add_u64 v[0:1], v[0:1], 0, v[116:117]
	s_waitcnt lgkmcnt(0)
	global_store_dwordx4 v[0:1], v[4:7], off
	ds_read_b128 v[0:3], v124 offset:10752
	s_nop 0
	v_add_u32_e32 v4, 16, v56
	v_ashrrev_i32_e32 v5, 31, v4
	v_lshlrev_b64 v[4:5], 12, v[4:5]
	v_lshl_add_u64 v[10:11], v[8:9], 0, v[4:5]
	v_lshl_add_u64 v[10:11], v[10:11], 0, v[118:119]
	ds_read_b128 v[4:7], v124 offset:11904
	s_waitcnt lgkmcnt(1)
	global_store_dwordx4 v[10:11], v[0:3], off
	s_nop 1
	v_add_u32_e32 v0, 24, v56
	v_ashrrev_i32_e32 v1, 31, v0
	v_lshlrev_b64 v[0:1], 12, v[0:1]
	v_lshl_add_u64 v[0:1], v[8:9], 0, v[0:1]
	v_lshl_add_u64 v[0:1], v[0:1], 0, v[116:117]
	s_waitcnt lgkmcnt(0)
	global_store_dwordx4 v[0:1], v[4:7], off
	s_waitcnt lgkmcnt(0)
	s_branch .LBB0_14

; #define LAS __attribute__((address_space(3)))
; #define LDS_WAIT() asm volatile("s_waitcnt lgkmcnt(0)" ::: "memory")
; __device__ __forceinline__ unsigned pk2(float lo, float hi) { return cvt_pk_bf16(lo, hi); }
;     __device__ __forceinline__ unsigned a(const pg8::Unit& u) const { return (unsigned)u.pm * (256u * K * 2u); }
;     __device__ __forceinline__ unsigned a(const pg8::Unit& u) const { return (unsigned)u.pm * (256u * K * 2u); }
;     __device__ __forceinline__ unsigned a(const pg8::Unit& u) const { return (unsigned)u.pm * (256u * K * 2u); }
;     __device__ __forceinline__ unsigned a(const pg8::Unit& u) const { return (unsigned)u.pm * (256u * K * 2u); }
;     __device__ __forceinline__ unsigned a(const pg8::Unit& u) const { return (unsigned)u.pm * (256u * K * 2u); }
; __device__ __forceinline__ void p0_prologue(const Frame& F) {
;     ...
; #pragma unroll
;             for (int i = 0; i < 4; ++i) {
;                 const int p8 = i * 64 + plane; const size_t e = e0 + (size_t)p8 * 8;
;                 u32x4 w; w.x = pk2(a[i][0], a[i][1]); w.y = pk2(a[i][2], a[i][3]); w.z = pk2(b[i][0], b[i][1]); w.w = pk2(b[i][2], b[i][3]);
;                 *(u32x4*)(F.XB + e) = w;
;                 const float xv[8] = {a[i][0], a[i][1], a[i][2], a[i][3], b[i][0], b[i][1], b[i][2], b[i][3]};
;                 *(unsigned*)(F.XB4 + e / 2) = q4x8(xv, X4_SCALE);
;                 LAS float* d = scr + (p8 >> 2) * 36 + (p8 & 3) * 8;
;                 *(LAS f32x4*)d = a[i]; *(LAS f32x4*)(d + 4) = b[i];
;             }
;             LDS_WAIT(); asm volatile("" ::: "memory");
.LBB0_51:
	v_cvt_pk_bf16_f32 v86, v28, v29
	v_cvt_pk_bf16_f32 v87, v30, v31
	v_cvt_pk_bf16_f32 v88, v24, v25
	v_cvt_pk_bf16_f32 v89, v26, v27
	v_add_f32_e32 v33, v28, v28
	v_add_f32_e32 v69, v29, v29
	global_store_dwordx4 v[72:73], v[86:89], off offset:-2048
	v_med3_f32 v33, v33, s35, v84
	v_med3_f32 v69, v69, s35, v84
	v_mov_b32_e32 v88, 0
	v_cvt_scalef32_pk_fp4_f32 v88, v33, v69, 1.0
	v_add_f32_e32 v33, v30, v30
	v_add_f32_e32 v69, v31, v31
	v_med3_f32 v33, v33, s35, v84
	v_med3_f32 v69, v69, s35, v84
	v_cvt_scalef32_pk_fp4_f32 v88, v33, v69, 1.0 op_sel:[0,0,1,0]
	v_add_f32_e32 v33, v24, v24
	v_add_f32_e32 v69, v25, v25
	v_med3_f32 v33, v33, s35, v84
	v_med3_f32 v69, v69, s35, v84
	v_lshl_add_u64 v[90:91], s[4:5], 0, v[78:79]
	v_cvt_scalef32_pk_fp4_f32 v88, v33, v69, 1.0 op_sel:[0,0,0,1]
	v_add_f32_e32 v33, v26, v26
	v_add_f32_e32 v69, v27, v27
	v_med3_f32 v33, v33, s35, v84
	v_med3_f32 v69, v69, s35, v84
	v_lshrrev_b64 v[86:87], 1, v[90:91]
	v_cvt_scalef32_pk_fp4_f32 v88, v33, v69, 1.0 op_sel:[0,0,1,1]
	v_lshl_add_u64 v[86:87], s[52:53], 0, v[86:87]
	global_store_dword v[86:87], v88, off
	ds_write_b128 v67, v[28:31]
	ds_write_b128 v67, v[24:27] offset:16
	v_cvt_pk_bf16_f32 v24, v20, v21
	v_cvt_pk_bf16_f32 v25, v22, v23
	v_cvt_pk_bf16_f32 v26, v16, v17
	v_cvt_pk_bf16_f32 v27, v18, v19
	global_store_dwordx4 v[72:73], v[24:27], off offset:-1024
	v_lshl_add_u64 v[28:29], v[90:91], 0, s[68:69]
	v_lshl_add_u64 v[86:87], v[70:71], 0, s[4:5]
	v_add_f32_e32 v24, v20, v20
	v_add_f32_e32 v25, v21, v21
	v_med3_f32 v24, v24, s35, v84
	v_med3_f32 v25, v25, s35, v84
	v_mov_b32_e32 v26, 0
	v_cvt_scalef32_pk_fp4_f32 v26, v24, v25, 1.0
	v_add_f32_e32 v24, v22, v22
	v_add_f32_e32 v25, v23, v23
	v_med3_f32 v24, v24, s35, v84
	v_med3_f32 v25, v25, s35, v84
	v_cvt_scalef32_pk_fp4_f32 v26, v24, v25, 1.0 op_sel:[0,0,1,0]
	v_add_f32_e32 v24, v16, v16
	v_add_f32_e32 v25, v17, v17
	v_med3_f32 v24, v24, s35, v84
	v_med3_f32 v25, v25, s35, v84
	v_cvt_scalef32_pk_fp4_f32 v26, v24, v25, 1.0 op_sel:[0,0,0,1]
	v_add_f32_e32 v24, v18, v18
	v_add_f32_e32 v25, v19, v19
	v_med3_f32 v24, v24, s35, v84
	v_med3_f32 v25, v25, s35, v84
	v_cvt_scalef32_pk_fp4_f32 v26, v24, v25, 1.0 op_sel:[0,0,1,1]
	v_lshrrev_b64 v[24:25], 1, v[28:29]
	v_lshl_add_u64 v[24:25], s[52:53], 0, v[24:25]
	global_store_dword v[24:25], v26, off
	ds_write_b128 v80, v[20:23]
	ds_write_b128 v80, v[16:19] offset:16
	v_cvt_pk_bf16_f32 v16, v12, v13
	v_cvt_pk_bf16_f32 v17, v14, v15
	v_cvt_pk_bf16_f32 v18, v8, v9
	v_cvt_pk_bf16_f32 v19, v10, v11
	global_store_dwordx4 v[72:73], v[16:19], off
	v_lshl_add_u64 v[20:21], v[90:91], 0, s[70:71]
	v_mov_b32_e32 v33, v32
	v_add_f32_e32 v16, v12, v12
	v_add_f32_e32 v17, v13, v13
	v_med3_f32 v16, v16, s35, v84
	v_med3_f32 v17, v17, s35, v84
	v_mov_b32_e32 v18, 0
	v_cvt_scalef32_pk_fp4_f32 v18, v16, v17, 1.0
	v_add_f32_e32 v16, v14, v14
	v_add_f32_e32 v17, v15, v15
	v_med3_f32 v16, v16, s35, v84
	v_med3_f32 v17, v17, s35, v84
	v_cvt_scalef32_pk_fp4_f32 v18, v16, v17, 1.0 op_sel:[0,0,1,0]
	v_add_f32_e32 v16, v8, v8
	v_add_f32_e32 v17, v9, v9
	v_med3_f32 v16, v16, s35, v84
	v_med3_f32 v17, v17, s35, v84
	v_cvt_scalef32_pk_fp4_f32 v18, v16, v17, 1.0 op_sel:[0,0,0,1]
	v_add_f32_e32 v16, v10, v10
	v_add_f32_e32 v17, v11, v11
	v_med3_f32 v16, v16, s35, v84
	v_med3_f32 v17, v17, s35, v84
	v_cvt_scalef32_pk_fp4_f32 v18, v16, v17, 1.0 op_sel:[0,0,1,1]
	v_lshrrev_b64 v[16:17], 1, v[20:21]
	v_lshl_add_u64 v[16:17], s[52:53], 0, v[16:17]
	global_store_dword v[16:17], v18, off
	ds_write_b128 v81, v[12:15]
	ds_write_b128 v81, v[8:11] offset:16
	v_cvt_pk_bf16_f32 v8, v4, v5
	v_cvt_pk_bf16_f32 v9, v6, v7
	v_cvt_pk_bf16_f32 v10, v0, v1
	v_cvt_pk_bf16_f32 v11, v2, v3
	global_store_dwordx4 v[72:73], v[8:11], off offset:1024
	v_lshl_add_u64 v[12:13], v[90:91], 0, s[76:77]
	s_add_u32 s16, s16, s58
	v_add_f32_e32 v8, v4, v4
	v_add_f32_e32 v9, v5, v5
	v_med3_f32 v8, v8, s35, v84
	v_med3_f32 v9, v9, s35, v84
	v_mov_b32_e32 v10, 0
	v_cvt_scalef32_pk_fp4_f32 v10, v8, v9, 1.0
	v_add_f32_e32 v8, v6, v6
	v_add_f32_e32 v9, v7, v7
	v_med3_f32 v8, v8, s35, v84
	v_med3_f32 v9, v9, s35, v84
	v_cvt_scalef32_pk_fp4_f32 v10, v8, v9, 1.0 op_sel:[0,0,1,0]
	v_add_f32_e32 v8, v0, v0
	v_add_f32_e32 v9, v1, v1
	v_med3_f32 v8, v8, s35, v84
	v_med3_f32 v9, v9, s35, v84
	v_cvt_scalef32_pk_fp4_f32 v10, v8, v9, 1.0 op_sel:[0,0,0,1]
	v_add_f32_e32 v8, v2, v2
	v_add_f32_e32 v9, v3, v3
	v_med3_f32 v8, v8, s35, v84
	v_med3_f32 v9, v9, s35, v84
	v_cvt_scalef32_pk_fp4_f32 v10, v8, v9, 1.0 op_sel:[0,0,1,1]
	v_lshrrev_b64 v[8:9], 1, v[12:13]
	v_lshl_add_u64 v[8:9], s[52:53], 0, v[8:9]
	global_store_dword v[8:9], v10, off
	ds_write_b128 v82, v[4:7]
	ds_write_b128 v82, v[0:3] offset:16
	s_waitcnt lgkmcnt(0)
; #define LAS __attribute__((address_space(3)))
;     __device__ __forceinline__ unsigned a(const pg8::Unit& u) const { return (unsigned)u.pm * (256u * K * 2u); }
;     __device__ __forceinline__ unsigned a(const pg8::Unit& u) const { return (unsigned)u.pm * (256u * K * 2u); }
;     __device__ __forceinline__ unsigned a(const pg8::Unit& u) const { return (unsigned)u.pm * (256u * K * 2u); }
;     __device__ __forceinline__ unsigned a(const pg8::Unit& u) const { return (unsigned)u.pm * (256u * K * 2u); }
;     __device__ __forceinline__ unsigned a(const pg8::Unit& u) const { return (unsigned)u.pm * (256u * K * 2u); }
; __device__ __forceinline__ void store_fp6_group(unsigned char* dst, const float (&v)[32], float scale) {
;     f32x16v a, b;
; #pragma unroll
;     for (int i = 0; i < 16; ++i) { a[i] = __builtin_amdgcn_fmed3f(v[i] * scale, -7.5f, 7.5f); b[i] = __builtin_amdgcn_fmed3f(v[16 + i] * scale, -7.5f, 7.5f); }
;     const u32x6v p = __builtin_amdgcn_cvt_scalef32_2xpk16_fp6_f32(a, b, 1.0f);
;     *(u32x4*)dst = (u32x4){p[0], p[1], p[2], p[3]};
;     *(u32x4*)(dst + 64) = (u32x4){p[4], p[5], 0u, 0u};
; __device__ __forceinline__ void p0_prologue(const Frame& F) {
;     ...
;             float v[32];
; #pragma unroll
;             for (int j = 0; j < 8; ++j) { const f32x4 t = *(const LAS f32x4*)(scr + plane * 36 + j * 4); v[4 * j] = t[0]; v[4 * j + 1] = t[1]; v[4 * j + 2] = t[2]; v[4 * j + 3] = t[3]; }
;             const size_t eg = e0 + (size_t)plane * 32;
;             store_fp6_group(F.XB8 + (eg >> 7) * 128 + ((eg >> 5) & 3) * 16, v, X6_SCALE);
	ds_read_b128 v[0:3], v83
	ds_read_b128 v[4:7], v83 offset:16
	ds_read_b128 v[8:11], v83 offset:32
	ds_read_b128 v[12:15], v83 offset:48
	ds_read_b128 v[16:19], v83 offset:64
	ds_read_b128 v[20:23], v83 offset:80
	ds_read_b128 v[24:27], v83 offset:96
	ds_read_b128 v[28:31], v83 offset:112
	s_waitcnt lgkmcnt(7)
	v_add_f32_e32 v0, v0, v0
	s_waitcnt lgkmcnt(3)
	v_add_f32_e32 v16, v16, v16
	v_add_f32_e32 v1, v1, v1
	v_add_f32_e32 v17, v17, v17
	v_add_f32_e32 v2, v2, v2
	v_add_f32_e32 v18, v18, v18
	v_add_f32_e32 v3, v3, v3
	v_add_f32_e32 v19, v19, v19
	v_add_f32_e32 v4, v4, v4
	s_waitcnt lgkmcnt(2)
	v_add_f32_e32 v20, v20, v20
	v_add_f32_e32 v5, v5, v5
	v_add_f32_e32 v21, v21, v21
	v_add_f32_e32 v6, v6, v6
	v_add_f32_e32 v22, v22, v22
	v_add_f32_e32 v7, v7, v7
	v_add_f32_e32 v23, v23, v23
	v_add_f32_e32 v8, v8, v8
	s_waitcnt lgkmcnt(1)
	v_add_f32_e32 v24, v24, v24
	v_add_f32_e32 v9, v9, v9
	v_add_f32_e32 v25, v25, v25
	v_add_f32_e32 v10, v10, v10
	v_add_f32_e32 v26, v26, v26
	v_add_f32_e32 v11, v11, v11
	v_add_f32_e32 v27, v27, v27
	v_add_f32_e32 v12, v12, v12
	s_waitcnt lgkmcnt(0)
	v_add_f32_e32 v28, v28, v28
	v_add_f32_e32 v13, v13, v13
	v_add_f32_e32 v29, v29, v29
	v_add_f32_e32 v14, v14, v14
	v_add_f32_e32 v30, v30, v30
	v_add_f32_e32 v15, v15, v15
	v_add_f32_e32 v31, v31, v31
	v_med3_f32 v0, v0, s3, v85
	v_med3_f32 v16, v16, s3, v85
	v_med3_f32 v1, v1, s3, v85
	v_med3_f32 v17, v17, s3, v85
	v_med3_f32 v2, v2, s3, v85
	v_med3_f32 v18, v18, s3, v85
	v_med3_f32 v3, v3, s3, v85
	v_med3_f32 v19, v19, s3, v85
	v_med3_f32 v4, v4, s3, v85
	v_med3_f32 v20, v20, s3, v85
	v_med3_f32 v5, v5, s3, v85
	v_med3_f32 v21, v21, s3, v85
	v_med3_f32 v6, v6, s3, v85
	v_med3_f32 v22, v22, s3, v85
	v_med3_f32 v7, v7, s3, v85
	v_med3_f32 v23, v23, s3, v85
	v_med3_f32 v8, v8, s3, v85
	v_med3_f32 v24, v24, s3, v85
	v_med3_f32 v9, v9, s3, v85
	v_med3_f32 v25, v25, s3, v85
	v_med3_f32 v10, v10, s3, v85
	v_med3_f32 v26, v26, s3, v85
	v_med3_f32 v11, v11, s3, v85
	v_med3_f32 v27, v27, s3, v85
	v_med3_f32 v12, v12, s3, v85
	v_med3_f32 v28, v28, s3, v85
	v_med3_f32 v13, v13, s3, v85
	v_med3_f32 v29, v29, s3, v85
	v_med3_f32 v14, v14, s3, v85
	v_med3_f32 v30, v30, s3, v85
	v_med3_f32 v15, v15, s3, v85
	v_med3_f32 v31, v31, s3, v85
	v_cvt_scalef32_2xpk16_fp6_f32 v[0:5], v[0:15], v[16:31], 1.0
	v_add_co_u32_e32 v6, vcc, s72, v86
	v_mov_b32_e32 v30, v4
	s_nop 0
	v_addc_co_u32_e32 v7, vcc, 0, v87, vcc
	v_mov_b32_e32 v31, v5
	v_mbcnt_lo_u32_b32 v8, -1, 0
	v_mbcnt_hi_u32_b32 v8, -1, v8
	v_and_b32_e32 v8, 3, v8
	v_mov_b32_e32 v9, s50
	v_bfe_u32 v15, v9, 4, 1
	v_bfe_u32 v14, v9, 7, 1
	v_bfe_u32 v12, v9, 1, 1
	v_and_b32_e32 v12, v12, v14
	v_mul_u32_u24_e32 v12, 0xfc0, v12
	v_bfe_u32 v9, v9, 3, 2
	v_and_b32_e32 v13, 1, v9
	v_sub_u32_e32 v9, 0, v9
	v_and_b32_e32 v9, 3, v9
	v_xor_b32_e32 v9, v8, v9
	v_sub_u32_e32 v9, v9, v8
	v_lshlrev_b32_e32 v10, 4, v9
	v_sub_u32_e32 v10, v10, v12
	v_ashrrev_i32_e32 v11, 31, v10
	v_lshl_add_u64 v[10:11], v[6:7], 0, v[10:11]
	global_store_dwordx4 v[10:11], v[0:3], off
	v_xor_b32_e32 v13, v14, v13
	v_lshlrev_b32_e32 v13, 5, v13
	v_lshlrev_b32_e32 v14, 18, v14
	v_sub_u32_e32 v13, v13, v14
	v_lshrrev_b32_e32 v14, 1, v8
	v_xor_b32_e32 v14, v14, v15
	v_lshl_add_u32 v13, v14, 4, v13
	v_and_b32_e32 v14, 1, v8
	v_lshl_add_u32 v13, v14, 3, v13
	v_lshlrev_b32_e32 v14, 4, v8
	v_sub_u32_e32 v12, v13, v14
	v_ashrrev_i32_e32 v13, 31, v12
	v_lshl_add_u64 v[12:13], v[6:7], 0, v[12:13]
	global_store_dwordx2 v[12:13], v[30:31], off offset:64
	s_waitcnt lgkmcnt(0)
	s_waitcnt vmcnt(17)
	v_mov_b64_e32 v[24:25], v[34:35]
	s_waitcnt vmcnt(15)
	v_mov_b64_e32 v[16:17], v[42:43]
	s_waitcnt vmcnt(12)
	v_mov_b64_e32 v[8:9], v[50:51]
	s_waitcnt vmcnt(10)
	v_mov_b64_e32 v[0:1], v[58:59]
	v_mov_b64_e32 v[28:29], v[38:39]
	v_mov_b64_e32 v[20:21], v[46:47]
	v_mov_b64_e32 v[12:13], v[54:55]
	v_mov_b64_e32 v[4:5], v[62:63]
	s_addc_u32 s17, s17, s59
	v_lshl_add_u64 v[70:71], v[70:71], 0, s[62:63]
	v_lshl_add_u64 v[78:79], v[78:79], 0, s[62:63]
	v_lshl_add_u64 v[72:73], v[72:73], 0, s[66:67]
	s_andn2_b64 vcc, exec, s[0:1]
	v_mov_b64_e32 v[26:27], v[36:37]
	v_mov_b64_e32 v[18:19], v[44:45]
	v_mov_b64_e32 v[10:11], v[52:53]
	v_mov_b64_e32 v[2:3], v[60:61]
	v_mov_b64_e32 v[30:31], v[40:41]
	v_mov_b64_e32 v[22:23], v[48:49]
	v_mov_b64_e32 v[14:15], v[56:57]
	v_mov_b64_e32 v[6:7], v[64:65]
	s_cbranch_vccz .LBB0_54

; #define LAS __attribute__((address_space(3)))
; #define PG8_STAGE(bufoff, rsrc, soff, voff) do { _Pragma("unroll") for (int _i = 0; _i < 2; ++_i) \
;         __builtin_amdgcn_raw_ptr_buffer_load_lds(rsrc, (LAS void*)(lds + (bufoff) + ldsw + _i * 8192), 16, (int)(voff)[0], (int)((soff) + (unsigned)_i * (64u * K * 2u)), 0, 0); } while (0)
; #define PG8_WAIT_V(n) asm volatile("s_waitcnt vmcnt(" #n ")" ::: "memory")
; #define PG8_BAR __builtin_amdgcn_s_barrier()
;     ...
;     for (int i = 0; i < 2; ++i) { int R, C; stage_rc(tid * 16 + i * 8192, R, C); const int Rb = Epi::PERM ? ((R & ~31) + perm32(R & 31)) : R;
;         voffA[i] = (unsigned)(R * K + C) * 2u; voffB[i] = (unsigned)(Rb * K + C) * 2u; }
;     constexpr unsigned kstep = BK * 2;
;     constexpr unsigned hstep = (unsigned)HALF * K * 2;
;     const __amdgpu_buffer_rsrc_t rA = __builtin_amdgcn_make_buffer_rsrc((void*)O.A, 0, -1, 0x00020000), rB = __builtin_amdgcn_make_buffer_rsrc((void*)O.B, 0, -1, 0x00020000);
;     const unsigned ldsw = (unsigned)wid * 1024u;
;     const int aoff = lds_byte(wr * 64 + fr, fq * 8), boff = lds_byte(wc * 32 + fr, fq * 8);
;     const LAS unsigned char* const la0 = lds + aoff; const LAS unsigned char* const lb0 = lds + boff;
;     ...
;         PG8_STAGE(PG8_SB(0, 0), rB, cB, voffB); PG8_STAGE(PG8_SB(0, 1), rB, cB + hstep, voffB); PG8_STAGE(PG8_SA(0, 0), rA, cA, voffA); PG8_STAGE(PG8_SA(0, 1), rA, cA + hstep, voffA);
;         if (wr == 1) PG8_BAR;
;         PG8_WAIT_V(2); PG8_BAR;
;         PG8_STAGE(PG8_SB(1, 0), rB, cB + kstep, voffB); PG8_STAGE(PG8_SA(1, 0), rA, cA + kstep, voffA); PG8_STAGE(PG8_SB(1, 1), rB, cB + hstep + kstep, voffB);
;         PG8_WAIT_V(6); PG8_BAR;
.LBB0_151:
	v_mbcnt_lo_u32_b32 v0, -1, 0
	v_mbcnt_hi_u32_b32 v0, -1, v0
	s_cmpk_lt_i32 s2, 0x1b00
	v_add_u32_e32 v0, s74, v0
	s_nop 0
	v_readfirstlane_b32 s1, v0
	s_cbranch_scc0 .LBB0_179
	s_add_u32 s64, s40, 0x10000000
	s_addc_u32 s0, s41, 0
	s_and_b32 s65, s0, 0xffff
	s_lshr_b32 s0, s11, 29
	s_add_i32 s0, s2, s0
	s_ashr_i32 s5, s1, 6
	s_ashr_i32 s7, s0, 3
	s_and_b32 s0, s0, -8
	s_and_b32 s61, s61, 0xffff
	s_ashr_i32 s4, s1, 8
	s_lshl_b32 s6, s5, 10
	s_sub_i32 s0, s2, s0
	s_cmp_lt_i32 s0, 0
	s_movk_i32 s79, 0x361
	s_cselect_b32 s8, s79, 0x360
	s_mul_i32 s0, s0, s8
	s_add_i32 s0, s0, s7
	s_mul_hi_i32 s7, s0, 0x38e38e39
	s_lshr_b32 s8, s7, 31
	s_ashr_i32 s7, s7, 6
	s_add_i32 s7, s7, s8
	s_lshl_b32 s8, s7, 2
	s_mulk_i32 s7, 0x120
	s_sub_i32 s0, s0, s7
	s_sext_i32_i16 s7, s0
	s_bfe_u32 s7, s7, 0x2001d
	v_ashrrev_i32_e32 v1, 3, v0
	s_add_i32 s7, s0, s7
	v_xor_b32_e32 v2, v1, v0
	v_lshlrev_b32_e32 v3, 1, v1
	v_lshrrev_b32_e32 v4, 2, v1
	s_sext_i32_i16 s9, s7
	s_and_b32 s7, s7, 0xfffc
	v_lshlrev_b32_e32 v2, 4, v2
	v_and_b32_e32 v3, 24, v3
	v_and_b32_e32 v4, 4, v4
	v_and_b32_e32 v5, 0xfffe3, v1
	s_sub_i32 s0, s0, s7
	s_add_i32 s69, s6, 0
	s_mov_b32 s67, 0x20000
	s_mov_b32 s66, -1
	v_and_b32_e32 v2, 0x70, v2
	v_or3_b32 v3, v5, v4, v3
	s_sext_i32_i16 s0, s0
	s_ashr_i32 s73, s9, 2
	s_add_i32 s71, s69, 0x10000
	s_mov_b32 s62, s66
	s_mov_b32 s63, s67
	s_waitcnt lgkmcnt(0)
	v_mbcnt_lo_u32_b32 v232, -1, 0
	v_mbcnt_hi_u32_b32 v232, -1, v232
	v_and_b32_e32 v233, 31, v232
	v_lshrrev_b32_e32 v234, 2, v233
	v_and_b32_e32 v235, 3, v232
	v_lshlrev_b32_e32 v235, 4, v235
	v_lshrrev_b32_e32 v236, 5, v232
	v_lshl_or_b32 v235, v236, 6, v235
	v_mov_b32_e32 v236, s1
	v_lshrrev_b32_e32 v236, 3, v236
	v_add_u32_e32 v234, v236, v234
	v_lshl_or_b32 v140, v234, 12, v235
	v_bfe_u32 v236, v234, 2, 2
	v_lshlrev_b32_e32 v236, 3, v236
	v_bfe_u32 v237, v234, 4, 1
	v_lshl_or_b32 v236, v237, 2, v236
	v_and_b32_e32 v237, 3, v234
	v_or_b32_e32 v236, v236, v237
	v_and_b32_e32 v237, 0xffffffe0, v234
	v_or_b32_e32 v236, v236, v237
	v_lshl_or_b32 v141, v236, 12, v235
	v_and_b32_e32 v236, 1, v234
	v_and_b32_e32 v237, 3, v232
	v_lshlrev_b32_e32 v237, 4, v237
	v_lshl_or_b32 v237, v236, 6, v237
	v_and_b32_e32 v238, -2, v234
	v_lshl_or_b32 v240, v238, 12, v237
	v_bfe_u32 v236, v238, 2, 2
	v_lshlrev_b32_e32 v236, 3, v236
	v_bfe_u32 v239, v238, 4, 1
	v_lshl_or_b32 v236, v239, 2, v236
	v_and_b32_e32 v239, 2, v238
	v_or_b32_e32 v236, v236, v239
	v_and_b32_e32 v239, 0xffffffe0, v238
	v_or_b32_e32 v236, v236, v239
	v_lshl_or_b32 v241, v236, 12, v237
	s_add_i32 s7, s8, s0
	s_lshl_b32 s0, s73, 20
	s_mov_b32 m0, s71
	s_add_i32 s82, s69, 0x12000
	buffer_load_dwordx4 v141, s[60:63], s0 offen lds
	s_or_b32 s6, s0, 0x40000
	s_mov_b32 m0, s82
	s_add_i32 s83, s69, 0x14000
	s_mov_b32 exec_hi, 0
	buffer_load_dwordx4 v241, s[60:63], s6 offen lds
	s_mov_b32 exec_hi, -1
	s_or_b32 s6, s0, 0x80000
	s_mov_b32 m0, s83
	s_add_i32 s84, s69, 0x16000
	buffer_load_dwordx4 v141, s[60:63], s6 offen lds
	s_or_b32 s6, s0, 0xc0000
	s_mov_b32 m0, s84
	s_nop 0
	s_mov_b32 exec_hi, 0
	buffer_load_dwordx4 v241, s[60:63], s6 offen lds
	s_mov_b32 exec_hi, -1
	s_lshl_b32 s35, s7, 20
	s_mov_b32 m0, s69
	s_add_i32 s85, s69, 0x2000
	buffer_load_dwordx4 v140, s[64:67], s35 offen lds
	s_or_b32 s6, s35, 0x40000
	s_mov_b32 m0, s85
	s_add_i32 s86, s69, 0x4000
	s_mov_b32 exec_hi, 0
	buffer_load_dwordx4 v240, s[64:67], s6 offen lds
	s_mov_b32 exec_hi, -1
	s_or_b32 s6, s35, 0x80000
	s_mov_b32 m0, s86
	s_add_i32 s87, s69, 0x6000
	buffer_load_dwordx4 v140, s[64:67], s6 offen lds
	s_or_b32 s6, s35, 0xc0000
	s_mov_b32 m0, s87
	s_cmp_eq_u32 s4, 1
	s_mov_b32 exec_hi, 0
	buffer_load_dwordx4 v240, s[64:67], s6 offen lds
	s_mov_b32 exec_hi, -1
	s_mov_b32 s78, s97
	v_and_b32_e32 v1, 7, v0
	s_cselect_b64 s[8:9], -1, 0
	s_cmp_lg_u32 s4, 1
	s_mov_b32 s88, 0
	s_cbranch_scc1 .LBB0_154
	s_barrier
; #define LAS __attribute__((address_space(3)))
; #define PG8_STAGE(bufoff, rsrc, soff, voff) do { _Pragma("unroll") for (int _i = 0; _i < 2; ++_i) \
;         __builtin_amdgcn_raw_ptr_buffer_load_lds(rsrc, (LAS void*)(lds + (bufoff) + ldsw + _i * 8192), 16, (int)(voff)[0], (int)((soff) + (unsigned)_i * (64u * K * 2u)), 0, 0); } while (0)
; #define PG8_WAIT_V(n) asm volatile("s_waitcnt vmcnt(" #n ")" ::: "memory")
; #define PG8_BAR __builtin_amdgcn_s_barrier()
;     ...
;     const unsigned ldsw = (unsigned)wid * 1024u;
;     const int aoff = lds_byte(wr * 64 + fr, fq * 8), boff = lds_byte(wc * 32 + fr, fq * 8);
;     const LAS unsigned char* const la0 = lds + aoff; const LAS unsigned char* const lb0 = lds + boff;
;     ...
;         PG8_STAGE(PG8_SB(1, 0), rB, cB + kstep, voffB); PG8_STAGE(PG8_SA(1, 0), rA, cA + kstep, voffA); PG8_STAGE(PG8_SB(1, 1), rB, cB + hstep + kstep, voffB);
;         PG8_WAIT_V(6); PG8_BAR;
.LBB0_154:
	s_lshl_b32 s5, s5, 5
	s_lshl_b32 s4, s4, 13
	s_and_b32 s5, s5, 0x60
	s_add_u32 s50, s40, 0x29000000
	s_addc_u32 s51, s41, 0
	s_add_i32 s89, s69, 0x18000
	s_or_b32 s6, s0, 0x80
	s_mov_b32 s62, s66
	s_mov_b32 s63, s67
	s_mov_b32 m0, s89
	s_add_i32 s90, s69, 0x1a000
	s_waitcnt vmcnt(2)
	s_barrier
	buffer_load_dwordx4 v141, s[60:63], s6 offen lds
	s_or_b32 s6, s0, 0x40080
	s_mov_b32 m0, s90
	s_add_i32 s91, s69, 0x8000
	s_mov_b32 exec_hi, 0
	buffer_load_dwordx4 v241, s[60:63], s6 offen lds
	s_mov_b32 exec_hi, -1
	s_or_b32 s6, s35, 0x80
	s_mov_b32 m0, s91
	s_add_i32 s92, s69, 0xa000
	buffer_load_dwordx4 v140, s[64:67], s6 offen lds
	s_or_b32 s6, s35, 0x40080
	s_mov_b32 m0, s92
	s_add_i32 s93, s69, 0x1c000
	s_mov_b32 exec_hi, 0
	buffer_load_dwordx4 v240, s[64:67], s6 offen lds
	s_mov_b32 exec_hi, -1
	s_or_b32 s6, s0, 0x80080
	s_mov_b32 m0, s93
	s_add_i32 s94, s69, 0x1e000
	buffer_load_dwordx4 v141, s[60:63], s6 offen lds
	s_or_b32 s6, s0, 0xc0080
	s_mov_b32 m0, s94
	v_and_b32_e32 v2, 15, v0
	s_mov_b32 exec_hi, 0
	buffer_load_dwordx4 v241, s[60:63], s6 offen lds
	s_mov_b32 exec_hi, -1
	v_lshlrev_b32_e32 v1, 4, v1
	v_and_b32_e32 v0, 48, v0
	v_lshlrev_b32_e32 v3, 7, v2
	v_or_b32_e32 v2, s5, v2
	v_xad_u32 v0, v1, v0, 0
	s_waitcnt vmcnt(6)
	s_add_i32 s95, s69, 0xc000
	v_writelane_b32 v255, s50, 25
	v_add3_u32 v142, v0, s4, v3
	v_lshl_add_u32 v0, v2, 7, v0
	v_mov_b32_e32 v1, 0x10000
	s_cmpk_lt_u32 s1, 0x100
	v_writelane_b32 v255, s51, 26
	v_xad_u32 v143, v0, 64, v1
	v_add_u32_e32 v144, 0x10000, v0
	v_add_u32_e32 v145, 0x10800, v0
	v_add_u32_e32 v146, 0x14000, v0
	v_add_u32_e32 v147, 0x14800, v0
	v_xor_b32_e32 v148, 64, v142
	v_add_u32_e32 v149, 0x18000, v0
	v_add_u32_e32 v150, 0x18800, v0
	v_add_u32_e32 v151, 0x1c000, v0
	v_add_u32_e32 v152, 0x1c800, v0
	s_cselect_b64 s[58:59], -1, 0
	v_mbcnt_lo_u32_b32 v232, -1, 0
	v_mbcnt_hi_u32_b32 v232, -1, v232
	v_and_b32_e32 v233, 15, v232
	v_lshrrev_b32_e32 v234, 4, v232
	v_lshrrev_b32_e32 v235, 2, v233
	v_sub_u32_e32 v235, 0, v235
	v_and_b32_e32 v235, 3, v235
	v_xor_b32_e32 v235, v234, v235
	v_lshlrev_b32_e32 v235, 4, v235
	v_lshrrev_b32_e32 v236, 3, v233
	v_lshlrev_b32_e32 v236, 10, v236
	v_and_b32_e32 v237, 7, v233
	v_lshl_add_u32 v238, v237, 6, v236
	v_add_u32_e32 v238, v238, v235
	v_add_u32_e32 v142, s4, v238
	s_lshl_b32 s99, s5, 7
	v_add_u32_e32 v0, s99, v238
	v_add_u32_e32 v144, 0x10000, v0
	v_add_u32_e32 v145, 0x10800, v0
	v_add_u32_e32 v146, 0x14000, v0
	v_add_u32_e32 v147, 0x14800, v0
	v_add_u32_e32 v149, 0x18000, v0
	v_add_u32_e32 v150, 0x18800, v0
	v_add_u32_e32 v151, 0x1c000, v0
	v_add_u32_e32 v152, 0x1c800, v0
	v_lshl_add_u32 v239, v237, 6, v236
	v_lshrrev_b32_e32 v237, 1, v234
	v_lshrrev_b32_e32 v235, 3, v233
	v_xor_b32_e32 v237, v237, v235
	v_lshl_add_u32 v239, v237, 4, v239
	v_and_b32_e32 v237, 1, v234
	v_lshl_add_u32 v239, v237, 3, v239
	v_add_u32_e32 v239, 0x200, v239
	v_bfe_u32 v235, v233, 2, 1
	s_lshr_b32 s100, s4, 13
	v_xor_b32_e32 v237, s100, v235
	v_lshl_add_u32 v148, v237, 5, v239
	s_lshr_b32 s98, s5, 6
	v_xor_b32_e32 v237, s98, v235
	v_lshl_add_u32 v143, v237, 5, v239
	s_bfe_u32 s100, s5, 0x10005
	s_lshl_b32 s100, s100, 12
	s_add_i32 s100, s100, 0x10000
	v_add_u32_e32 v143, s100, v143
	s_add_i32 s96, s69, 0xe000
	v_mov_b64_e32 v[128:129], 0x1b00
	v_mov_b64_e32 v[130:131], 0x1aff
	v_mov_b32_e32 v133, 0
	s_mov_b32 s68, 0x3b800000
	s_mov_b32 s97, 0x100000
	s_movk_i32 s1, 0x1fef
	s_movk_i32 s72, 0x1fff
	s_mov_b32 s70, 0x3a0293ee
	s_barrier
	s_branch .LBB0_157

; #define PG8_STAGE(bufoff, rsrc, soff, voff) do { _Pragma("unroll") for (int _i = 0; _i < 2; ++_i) \
;         __builtin_amdgcn_raw_ptr_buffer_load_lds(rsrc, (LAS void*)(lds + (bufoff) + ldsw + _i * 8192), 16, (int)(voff)[0], (int)((soff) + (unsigned)_i * (64u * K * 2u)), 0, 0); } while (0)
; #define PG8_WAIT_VN(n) asm volatile("s_waitcnt vmcnt(%0)" :: "n"(n) : "memory")
; #define PG8_WAIT_V(n) asm volatile("s_waitcnt vmcnt(" #n ")" ::: "memory")
; #define PG8_WAIT_L(n) asm volatile("s_waitcnt lgkmcnt(" #n ")" ::: "memory")
; #define PG8_BAR __builtin_amdgcn_s_barrier()
; #define PG8_SCHED __builtin_amdgcn_sched_barrier(0)
;     ...
;             } else if constexpr (SP2) {
;             const bool relax = RELAX_EPI_WAIT && (t == 0) && (ui > 0);
;             PG8_LDB(B0, 0, 0); PG8_LDB(B1, 0, 1); PG8_SCHED; PG8_LDA(At, 0, 0); PG8_STAGE(PG8_SA(1, 1), rA, a1 + hstep, voffA);
;             if (relax) PG8_WAIT_VN(VRELAX); else PG8_WAIT_V(8); PG8_WAIT_L(0); PG8_BAR; PG8_MMA(0, 0, At, B0); PG8_MMA(0, 1, At, B1); PG8_BAR; PG8_SCHED;
;             PG8_LDA(At, 0, 1); PG8_STAGE(PG8_SB(0, 0), rB, b2, voffB); PG8_STAGE(PG8_SB(0, 1), rB, b2 + hstep, voffB); PG8_STAGE(PG8_SA(0, 0), rA, a2, voffA);
;             if (relax) PG8_WAIT_VN(VRELAX); else PG8_WAIT_V(8); PG8_WAIT_L(0); PG8_BAR; PG8_MMA(1, 0, At, B0); PG8_MMA(1, 1, At, B1); PG8_BAR; PG8_SCHED;
.LBB0_160:
	v_mov_b32_e32 v132, v143
	ds_read_b128 v[134:137], v144
	ds_read_b64 v[138:139], v132 offset:0
	ds_read_b128 v[154:157], v145
	ds_read_b64 v[158:159], v132 offset:0x800
	v_mov_b32_e32 v132, v143
	ds_read_b128 v[160:163], v146
	ds_read_b64 v[164:165], v132 offset:0x4000
	ds_read_b128 v[166:169], v147
	ds_read_b64 v[170:171], v132 offset:0x4800
	s_add_i32 s0, vcc_lo, 0xfff40080
	s_cmp_eq_u32 s54, 28
	s_cselect_b32 s55, s76, s0
	v_mov_b32_e32 v132, v148
	ds_read_b128 v[172:175], v142
	ds_read_b64 v[176:177], v132 offset:0
	ds_read_b128 v[178:181], v142 offset:2048
	ds_read_b64 v[182:183], v132 offset:0x800
	ds_read_b128 v[184:187], v142 offset:4096
	ds_read_b64 v[188:189], v132 offset:0x1000
	s_mov_b32 m0, s95
	ds_read_b128 v[190:193], v142 offset:6144
	ds_read_b64 v[194:195], v132 offset:0x1800
	s_cselect_b32 s35, s77, vcc_hi
	s_add_i32 s0, vcc_lo, 0xfffc0000
	buffer_load_dwordx4 v140, s[64:67], s0 offen lds
	s_mov_b32 m0, s96
	s_or_b32 s0, s55, 0x80
	s_mov_b32 exec_hi, 0
	buffer_load_dwordx4 v240, s[64:67], vcc_lo offen lds
	s_mov_b32 exec_hi, -1
	s_waitcnt vmcnt(8)
	s_waitcnt lgkmcnt(0)
	s_barrier
	s_setprio 1
	s_waitcnt lgkmcnt(3)
	v_mfma_f32_16x16x128_f8f6f4 v[124:127], v[134:139], v[172:177], v[124:127] cbsz:2 blgp:2
	v_mfma_f32_16x16x128_f8f6f4 v[120:123], v[154:159], v[172:177], v[120:123] cbsz:2 blgp:2
	s_waitcnt lgkmcnt(2)
	v_mfma_f32_16x16x128_f8f6f4 v[108:111], v[134:139], v[178:183], v[108:111] cbsz:2 blgp:2
	v_mfma_f32_16x16x128_f8f6f4 v[104:107], v[154:159], v[178:183], v[104:107] cbsz:2 blgp:2
	s_waitcnt lgkmcnt(1)
	v_mfma_f32_16x16x128_f8f6f4 v[92:95], v[134:139], v[184:189], v[92:95] cbsz:2 blgp:2
	v_mfma_f32_16x16x128_f8f6f4 v[88:91], v[154:159], v[184:189], v[88:91] cbsz:2 blgp:2
	s_waitcnt lgkmcnt(0)
	v_mfma_f32_16x16x128_f8f6f4 v[196:199], v[134:139], v[190:195], v[76:79] cbsz:2 blgp:2
	v_mfma_f32_16x16x128_f8f6f4 v[200:203], v[154:159], v[190:195], v[72:75] cbsz:2 blgp:2
	s_setprio 0
	s_setprio 1
	v_mfma_f32_16x16x128_f8f6f4 v[116:119], v[160:165], v[172:177], v[116:119] cbsz:2 blgp:2
	v_mfma_f32_16x16x128_f8f6f4 v[112:115], v[166:171], v[172:177], v[112:115] cbsz:2 blgp:2
	v_mfma_f32_16x16x128_f8f6f4 v[100:103], v[160:165], v[178:183], v[100:103] cbsz:2 blgp:2
	v_mfma_f32_16x16x128_f8f6f4 v[96:99], v[166:171], v[178:183], v[96:99] cbsz:2 blgp:2
	v_mfma_f32_16x16x128_f8f6f4 v[172:175], v[160:165], v[184:189], v[84:87] cbsz:2 blgp:2
	v_mfma_f32_16x16x128_f8f6f4 v[176:179], v[166:171], v[184:189], v[80:83] cbsz:2 blgp:2
	v_mfma_f32_16x16x128_f8f6f4 v[180:183], v[160:165], v[190:195], v[68:71] cbsz:2 blgp:2
	v_mfma_f32_16x16x128_f8f6f4 v[184:187], v[166:171], v[190:195], v[64:67] cbsz:2 blgp:2
	s_setprio 0
	s_barrier
	v_mov_b32_e32 v86, v148
	ds_read_b128 v[64:67], v142 offset:16384
	ds_read_b64 v[68:69], v86 offset:0x4000
	ds_read_b128 v[70:73], v142 offset:18432
	ds_read_b64 v[74:75], v86 offset:0x4800
	ds_read_b128 v[76:79], v142 offset:20480
	ds_read_b64 v[80:81], v86 offset:0x5000
	s_mov_b32 m0, s71
	ds_read_b128 v[82:85], v142 offset:22528
	ds_read_b64 v[86:87], v86 offset:0x5800
	s_mov_b32 s62, s66
	s_mov_b32 s63, s67
	buffer_load_dwordx4 v141, s[60:63], s35 offen lds
	s_add_i32 s50, s35, 0x40000
	s_mov_b32 m0, s82
	s_nop 0
	s_mov_b32 exec_hi, 0
	buffer_load_dwordx4 v241, s[60:63], s50 offen lds
	s_mov_b32 exec_hi, -1
	s_add_i32 s50, s35, 0x80000
	s_mov_b32 m0, s83
	s_nop 0
	buffer_load_dwordx4 v141, s[60:63], s50 offen lds
	s_add_i32 s50, s35, 0xc0000
	s_mov_b32 m0, s84
	s_nop 0
	s_mov_b32 exec_hi, 0
	buffer_load_dwordx4 v241, s[60:63], s50 offen lds
	s_mov_b32 exec_hi, -1
	s_mov_b32 m0, s69
	s_add_i32 s50, s55, 0x40000
	buffer_load_dwordx4 v140, s[64:67], s55 offen lds
	s_mov_b32 m0, s85
	s_nop 0
	s_mov_b32 exec_hi, 0
	buffer_load_dwordx4 v240, s[64:67], s50 offen lds
	s_mov_b32 exec_hi, -1
	s_waitcnt vmcnt(8)
	s_waitcnt lgkmcnt(0)
	s_barrier
	s_setprio 1
	s_waitcnt lgkmcnt(3)
	v_mfma_f32_16x16x128_f8f6f4 v[60:63], v[134:139], v[64:69], v[60:63] cbsz:2 blgp:2
	v_mfma_f32_16x16x128_f8f6f4 v[56:59], v[154:159], v[64:69], v[56:59] cbsz:2 blgp:2
	s_waitcnt lgkmcnt(2)
	v_mfma_f32_16x16x128_f8f6f4 v[44:47], v[134:139], v[70:75], v[44:47] cbsz:2 blgp:2
	v_mfma_f32_16x16x128_f8f6f4 v[40:43], v[154:159], v[70:75], v[40:43] cbsz:2 blgp:2
	s_waitcnt lgkmcnt(1)
	v_mfma_f32_16x16x128_f8f6f4 v[188:191], v[134:139], v[76:81], v[28:31] cbsz:2 blgp:2
	v_mfma_f32_16x16x128_f8f6f4 v[192:195], v[154:159], v[76:81], v[24:27] cbsz:2 blgp:2
	s_waitcnt lgkmcnt(0)
	v_mfma_f32_16x16x128_f8f6f4 v[204:207], v[134:139], v[82:87], v[12:15] cbsz:2 blgp:2
	v_mfma_f32_16x16x128_f8f6f4 v[208:211], v[154:159], v[82:87], v[8:11] cbsz:2 blgp:2
	s_setprio 0
	s_setprio 1
	v_mfma_f32_16x16x128_f8f6f4 v[52:55], v[160:165], v[64:69], v[52:55] cbsz:2 blgp:2
	v_mfma_f32_16x16x128_f8f6f4 v[48:51], v[166:171], v[64:69], v[48:51] cbsz:2 blgp:2
	v_mfma_f32_16x16x128_f8f6f4 v[36:39], v[160:165], v[70:75], v[36:39] cbsz:2 blgp:2
	v_mfma_f32_16x16x128_f8f6f4 v[212:215], v[166:171], v[70:75], v[32:35] cbsz:2 blgp:2
	v_mfma_f32_16x16x128_f8f6f4 v[216:219], v[160:165], v[76:81], v[20:23] cbsz:2 blgp:2
	v_mfma_f32_16x16x128_f8f6f4 v[220:223], v[166:171], v[76:81], v[16:19] cbsz:2 blgp:2
	v_mfma_f32_16x16x128_f8f6f4 v[224:227], v[160:165], v[82:87], v[4:7] cbsz:2 blgp:2
	v_mfma_f32_16x16x128_f8f6f4 v[228:231], v[166:171], v[82:87], v[0:3] cbsz:2 blgp:2
	s_setprio 0
	s_barrier
; #define PG8_STAGE(bufoff, rsrc, soff, voff) do { _Pragma("unroll") for (int _i = 0; _i < 2; ++_i) \
;         __builtin_amdgcn_raw_ptr_buffer_load_lds(rsrc, (LAS void*)(lds + (bufoff) + ldsw + _i * 8192), 16, (int)(voff)[0], (int)((soff) + (unsigned)_i * (64u * K * 2u)), 0, 0); } while (0)
; #define PG8_WAIT_VN(n) asm volatile("s_waitcnt vmcnt(%0)" :: "n"(n) : "memory")
; #define PG8_WAIT_V(n) asm volatile("s_waitcnt vmcnt(" #n ")" ::: "memory")
; #define PG8_WAIT_L(n) asm volatile("s_waitcnt lgkmcnt(" #n ")" ::: "memory")
; #define PG8_BAR __builtin_amdgcn_s_barrier()
; #define PG8_SCHED __builtin_amdgcn_sched_barrier(0)
;     ...
;             if (relax) PG8_WAIT_VN(VRELAX); else PG8_WAIT_V(8); PG8_WAIT_L(0); PG8_BAR; PG8_MMA(1, 0, At, B0); PG8_MMA(1, 1, At, B1); PG8_BAR; PG8_SCHED;
;             PG8_LDB(B0, 1, 0); PG8_LDB(B1, 1, 1); PG8_SCHED; PG8_LDA(At, 1, 0); PG8_STAGE(PG8_SA(0, 1), rA, a2 + hstep, voffA);
;             PG8_WAIT_V(8); PG8_WAIT_L(0); PG8_BAR; PG8_MMA(0, 0, At, B0); PG8_MMA(0, 1, At, B1); PG8_BAR; PG8_SCHED;
;             PG8_LDA(At, 1, 1); PG8_STAGE(PG8_SB(1, 0), rB, b3, voffB); PG8_STAGE(PG8_SB(1, 1), rB, b3 + hstep, voffB); PG8_STAGE(PG8_SA(1, 0), rA, a3, voffA);
;             PG8_WAIT_V(8); PG8_WAIT_L(0); PG8_BAR; PG8_MMA(1, 0, At, B0); PG8_MMA(1, 1, At, B1); PG8_BAR; PG8_SCHED;
	v_mov_b32_e32 v10, v143
	ds_read_b128 v[0:3], v149
	ds_read_b64 v[4:5], v10 offset:0x8000
	v_mov_b32_e32 v12, v143
	ds_read_b128 v[6:9], v150
	ds_read_b64 v[10:11], v10 offset:0x8800
	ds_read_b128 v[134:137], v151
	ds_read_b64 v[138:139], v12 offset:0xc000
	ds_read_b128 v[154:157], v152
	ds_read_b64 v[158:159], v12 offset:0xc800
	v_mov_b32_e32 v34, v148
	ds_read_b128 v[12:15], v142 offset:32768
	ds_read_b64 v[16:17], v34 offset:0x8000
	ds_read_b128 v[18:21], v142 offset:34816
	ds_read_b64 v[22:23], v34 offset:0x8800
	ds_read_b128 v[24:27], v142 offset:36864
	ds_read_b64 v[28:29], v34 offset:0x9000
	s_mov_b32 m0, s86
	ds_read_b128 v[30:33], v142 offset:38912
	ds_read_b64 v[34:35], v34 offset:0x9800
	s_add_i32 s50, s55, 0x80000
	buffer_load_dwordx4 v140, s[64:67], s50 offen lds
	s_add_i32 s50, s55, 0xc0000
	s_mov_b32 m0, s87
	s_nop 0
	s_mov_b32 exec_hi, 0
	buffer_load_dwordx4 v240, s[64:67], s50 offen lds
	s_mov_b32 exec_hi, -1
	s_waitcnt vmcnt(8)
	s_waitcnt lgkmcnt(0)
	s_barrier
	s_setprio 1
	s_waitcnt lgkmcnt(3)
	v_mfma_f32_16x16x128_f8f6f4 v[124:127], v[0:5], v[12:17], v[124:127] cbsz:2 blgp:2
	v_mfma_f32_16x16x128_f8f6f4 v[120:123], v[6:11], v[12:17], v[120:123] cbsz:2 blgp:2
	s_waitcnt lgkmcnt(2)
	v_mfma_f32_16x16x128_f8f6f4 v[108:111], v[0:5], v[18:23], v[108:111] cbsz:2 blgp:2
	v_mfma_f32_16x16x128_f8f6f4 v[104:107], v[6:11], v[18:23], v[104:107] cbsz:2 blgp:2
	s_waitcnt lgkmcnt(1)
	v_mfma_f32_16x16x128_f8f6f4 v[92:95], v[0:5], v[24:29], v[92:95] cbsz:2 blgp:2
	v_mfma_f32_16x16x128_f8f6f4 v[88:91], v[6:11], v[24:29], v[88:91] cbsz:2 blgp:2
	s_waitcnt lgkmcnt(0)
	v_mfma_f32_16x16x128_f8f6f4 v[76:79], v[0:5], v[30:35], v[196:199] cbsz:2 blgp:2
	v_mfma_f32_16x16x128_f8f6f4 v[72:75], v[6:11], v[30:35], v[200:203] cbsz:2 blgp:2
	s_setprio 0
	s_setprio 1
	v_mfma_f32_16x16x128_f8f6f4 v[116:119], v[134:139], v[12:17], v[116:119] cbsz:2 blgp:2
	s_or_b32 s50, s35, 0x80
	v_mfma_f32_16x16x128_f8f6f4 v[112:115], v[154:159], v[12:17], v[112:115] cbsz:2 blgp:2
	v_mfma_f32_16x16x128_f8f6f4 v[100:103], v[134:139], v[18:23], v[100:103] cbsz:2 blgp:2
	v_mfma_f32_16x16x128_f8f6f4 v[96:99], v[154:159], v[18:23], v[96:99] cbsz:2 blgp:2
	v_mfma_f32_16x16x128_f8f6f4 v[84:87], v[134:139], v[24:29], v[172:175] cbsz:2 blgp:2
	v_mfma_f32_16x16x128_f8f6f4 v[80:83], v[154:159], v[24:29], v[176:179] cbsz:2 blgp:2
	v_mfma_f32_16x16x128_f8f6f4 v[68:71], v[134:139], v[30:35], v[180:183] cbsz:2 blgp:2
	v_mfma_f32_16x16x128_f8f6f4 v[64:67], v[154:159], v[30:35], v[184:187] cbsz:2 blgp:2
	s_setprio 0
	s_barrier
	v_mov_b32_e32 v12, v148
	ds_read_b128 v[16:19], v142 offset:49152
	ds_read_b64 v[20:21], v12 offset:0xc000
	ds_read_b128 v[160:163], v142 offset:51200
	ds_read_b64 v[164:165], v12 offset:0xc800
	ds_read_b128 v[166:169], v142 offset:53248
	ds_read_b64 v[170:171], v12 offset:0xd000
	s_mov_b32 m0, s89
	ds_read_b128 v[172:175], v142 offset:55296
	ds_read_b64 v[176:177], v12 offset:0xd800
	buffer_load_dwordx4 v141, s[60:63], s50 offen lds
	s_add_i32 s50, s35, 0x40080
	s_mov_b32 m0, s90
	s_add_i32 s55, s55, 0x40080
	s_mov_b32 exec_hi, 0
	buffer_load_dwordx4 v241, s[60:63], s50 offen lds
	s_mov_b32 exec_hi, -1
	s_add_i32 s50, s35, 0x80080
	s_mov_b32 m0, s93
	s_add_i32 s35, s35, 0xc0080
	buffer_load_dwordx4 v141, s[60:63], s50 offen lds
	s_mov_b32 m0, s94
	s_nop 0
	s_mov_b32 exec_hi, 0
	buffer_load_dwordx4 v241, s[60:63], s35 offen lds
	s_mov_b32 exec_hi, -1
	s_mov_b32 m0, s91
	s_nop 0
	buffer_load_dwordx4 v140, s[64:67], s0 offen lds
	s_mov_b32 m0, s92
	s_nop 0
	s_mov_b32 exec_hi, 0
	buffer_load_dwordx4 v240, s[64:67], s55 offen lds
	s_mov_b32 exec_hi, -1
	s_waitcnt vmcnt(8)
	s_waitcnt lgkmcnt(0)
	s_barrier
	s_setprio 1
	s_waitcnt lgkmcnt(3)
	v_mfma_f32_16x16x128_f8f6f4 v[60:63], v[0:5], v[16:21], v[60:63] cbsz:2 blgp:2
	v_mfma_f32_16x16x128_f8f6f4 v[56:59], v[6:11], v[16:21], v[56:59] cbsz:2 blgp:2
	s_waitcnt lgkmcnt(2)
	v_mfma_f32_16x16x128_f8f6f4 v[44:47], v[0:5], v[160:165], v[44:47] cbsz:2 blgp:2
	v_mfma_f32_16x16x128_f8f6f4 v[40:43], v[6:11], v[160:165], v[40:43] cbsz:2 blgp:2
	s_waitcnt lgkmcnt(1)
	v_mfma_f32_16x16x128_f8f6f4 v[28:31], v[0:5], v[166:171], v[188:191] cbsz:2 blgp:2
	v_mfma_f32_16x16x128_f8f6f4 v[24:27], v[6:11], v[166:171], v[192:195] cbsz:2 blgp:2
	s_waitcnt lgkmcnt(0)
	v_mfma_f32_16x16x128_f8f6f4 v[12:15], v[0:5], v[172:177], v[204:207] cbsz:2 blgp:2
	v_mfma_f32_16x16x128_f8f6f4 v[8:11], v[6:11], v[172:177], v[208:211] cbsz:2 blgp:2
	s_setprio 0
	s_setprio 1
	v_mfma_f32_16x16x128_f8f6f4 v[52:55], v[134:139], v[16:21], v[52:55] cbsz:2 blgp:2
	v_mfma_f32_16x16x128_f8f6f4 v[48:51], v[154:159], v[16:21], v[48:51] cbsz:2 blgp:2
	v_mfma_f32_16x16x128_f8f6f4 v[36:39], v[134:139], v[160:165], v[36:39] cbsz:2 blgp:2
	v_mfma_f32_16x16x128_f8f6f4 v[32:35], v[154:159], v[160:165], v[212:215] cbsz:2 blgp:2
	v_mfma_f32_16x16x128_f8f6f4 v[20:23], v[134:139], v[166:171], v[216:219] cbsz:2 blgp:2
	v_mfma_f32_16x16x128_f8f6f4 v[16:19], v[154:159], v[166:171], v[220:223] cbsz:2 blgp:2
	v_mfma_f32_16x16x128_f8f6f4 v[4:7], v[134:139], v[172:177], v[224:227] cbsz:2 blgp:2
	v_mfma_f32_16x16x128_f8f6f4 v[0:3], v[154:159], v[172:177], v[228:231] cbsz:2 blgp:2
	s_setprio 0
	s_barrier
	s_add_i32 s54, s54, 2
	s_addk_i32 vcc_lo, 0x100
	s_addk_i32 vcc_hi, 0x100
	s_cmp_gt_u32 s54, 29
	s_cbranch_scc0 .LBB0_160
	s_and_b64 vcc, exec, s[58:59]
	s_cbranch_vccz .LBB0_163
	s_barrier
